# attention out-proj moved onto the 256x128 k-blocked GEMM path; phase-5 (stick-breaking / linear-attention) epilogues store hn k-blocked; wt_out converted k-blocked
# speedup vs baseline: 1.1391x; 1.0098x over previous
.LBB0_21:
	v_readlane_b32 s6, v244, 1
	v_readlane_b32 s7, v244, 2
	s_cmp_lt_u32 s70, 11
	v_readlane_b32 s0, v244, 3
	s_mov_b32 s71, s6
	s_cselect_b64 s[6:7], -1, 0
	s_add_i32 s20, s70, -9
	v_readlane_b32 s1, v244, 4
	v_readlane_b32 s3, v244, 0
	s_cmp_gt_u32 s70, 10
	s_cselect_b64 s[22:23], -1, 0
	s_waitcnt lgkmcnt(0)
	s_load_dwordx2 s[24:25], s[0:1], 0xb8
	s_and_b64 s[18:19], s[22:23], exec
	s_cselect_b32 s18, s20, s70
	s_cmp_lt_u32 s70, 2
	s_cselect_b32 s19, s70, s18
	s_cmp_eq_u32 s19, 0
	s_cbranch_scc1 .Lp0_entry
	s_cmp_eq_u32 s19, 9
	s_cbranch_scc1 .Lgy_entry
	s_cmp_eq_u32 s19, 8
	s_cbranch_scc1 .Lup_entry
	s_cmp_eq_u32 s19, 6
	s_cbranch_scc1 .Lop_entry
	s_cmp_eq_u32 s19, 2
	s_cbranch_scc1 .Lpj_entry
	s_cmp_lt_i32 s19, 5
	s_cbranch_scc1 .LBB0_46
	s_and_b64 s[20:21], s[22:23], exec
	s_cselect_b32 s18, 0x18000, 0
	s_waitcnt lgkmcnt(0)
	s_add_u32 s66, s24, s18
	s_addc_u32 s80, s25, 0
	s_cmp_gt_i32 s19, 7
	s_cbranch_scc0 .LBB0_47
	s_cmp_gt_i32 s19, 8
	s_cbranch_scc0 .LBB0_48
	s_cmp_gt_i32 s19, 9
	s_cbranch_scc0 .LBB0_64
	s_mov_b64 s[20:21], 0
	s_mov_b64 s[24:25], 0
	s_cmp_eq_u32 s19, 10
	v_writelane_b32 v244, s20, 56
	s_nop 1
	v_writelane_b32 v244, s21, 57
	s_cbranch_scc0 .LBB0_65
	s_load_dwordx2 s[30:31], s[0:1], 0x68
	s_and_b64 vcc, exec, s[6:7]
	s_cbranch_vccz .LBB0_334
	s_lshl_b32 s18, s71, 2
	s_abs_i32 s6, s18
	v_cvt_f32_u32_e32 v0, s6
	s_waitcnt vmcnt(0)
	v_mov_b32_e32 v34, v154
	v_mov_b32_e32 v2, v154
	s_sub_i32 s26, 0, s6
	v_rcp_iflag_f32_e32 v0, v0
	s_nop 0
	v_mul_f32_e32 v0, 0x4f7ffffe, v0
	v_cvt_u32_f32_e32 v0, v0
	v_readfirstlane_b32 s7, v2
	s_ashr_i32 s20, s7, 6
	s_add_i32 s7, s18, 0x3fff
	v_readfirstlane_b32 s27, v0
	s_mul_i32 s26, s26, s27
	s_mul_hi_u32 s26, s27, s26
	s_xor_b32 s21, s7, s18
	s_abs_i32 s7, s7
	s_add_i32 s27, s27, s26
	s_mul_hi_u32 s26, s7, s27
	s_mul_i32 s27, s26, s6
	s_sub_i32 s7, s7, s27
	s_ashr_i32 s21, s21, 31
	s_add_i32 s27, s26, 1
	s_sub_i32 s28, s7, s6
	s_cmp_ge_u32 s7, s6
	s_cselect_b32 s26, s27, s26
	s_cselect_b32 s7, s28, s7
	s_add_i32 s27, s26, 1
	s_cmp_ge_u32 s7, s6
	s_cselect_b32 s6, s27, s26
	s_xor_b32 s6, s6, s21
	s_lshl_b32 s52, s3, 2
	s_sub_i32 s7, s6, s21
	s_add_i32 s6, s20, s52
	s_mul_i32 s6, s6, s7
	s_cmpk_gt_i32 s6, 0x3fff
	s_cbranch_scc1 .LBB0_335
	s_load_dwordx2 s[26:27], s[0:1], 0x110
	s_ashr_i32 s20, s6, 12
	s_mulk_i32 s20, 0x1800
	v_lshlrev_b32_e32 v0, 2, v34
	v_and_b32_e32 v35, 0xfc, v0
	s_waitcnt lgkmcnt(0)
	s_cmp_lg_u64 s[26:27], 0
	s_cselect_b64 s[40:41], -1, 0
	s_ashr_i32 s21, s20, 31
	s_lshl_b64 s[34:35], s[20:21], 2
	s_add_u32 s20, s66, s34
	s_addc_u32 s21, s80, s35
	s_add_u32 s36, s20, 0x5000
	s_addc_u32 s37, s21, 0
	s_and_b64 vcc, exec, s[40:41]
	v_lshlrev_b32_e32 v0, 2, v35
	s_cbranch_vccz .LBB0_30
	v_lshl_add_u64 v[10:11], s[36:37], 0, v[0:1]
	v_add_co_u32_e32 v6, vcc, 0x30000, v10
	global_load_dwordx4 v[2:5], v0, s[36:37]
	s_nop 0
	v_addc_co_u32_e32 v7, vcc, 0, v11, vcc
	global_load_dwordx4 v[6:9], v[6:7], off
	s_waitcnt vmcnt(0)
	v_pk_add_f32 v[6:7], v[2:3], v[6:7]
	v_add_co_u32_e32 v2, vcc, 0x60000, v10
	v_pk_add_f32 v[8:9], v[4:5], v[8:9]
	s_nop 0
	v_addc_co_u32_e32 v3, vcc, 0, v11, vcc
	global_load_dwordx4 v[2:5], v[2:3], off
	s_waitcnt vmcnt(0)
	v_pk_add_f32 v[6:7], v[6:7], v[2:3]
	v_add_co_u32_e32 v2, vcc, 0x90000, v10
	v_pk_add_f32 v[8:9], v[8:9], v[4:5]
	s_nop 0
	v_addc_co_u32_e32 v3, vcc, 0, v11, vcc
	global_load_dwordx4 v[2:5], v[2:3], off
	s_waitcnt vmcnt(0)
	v_pk_add_f32 v[68:69], v[8:9], v[4:5]
	v_pk_add_f32 v[66:67], v[6:7], v[2:3]
	global_load_dwordx4 v[2:5], v0, s[30:31]

.LBB0_179:
	s_or_b64 exec, exec, s[92:93]
	s_lshl_b64 s[6:7], s[34:35], 6
	s_add_u32 s6, s48, s6
	s_addc_u32 s7, s49, s7
	s_lshl_b32 s36, s36, 14
	s_add_u32 s6, s6, s36
	s_addc_u32 s7, s7, 0
	s_add_u32 s6, s6, 0xc00000
	s_addc_u32 s7, s7, 0
	v_lshlrev_b32_e32 v0, 1, v68
	v_lshl_or_b32 v0, v55, 8, v0
	v_add_u32_e32 v2, 0x100000, v0
	v_cvt_pk_bf16_f32 v4, v38, s0
	global_store_short v0, v4, s[6:7]
	v_cvt_pk_bf16_f32 v4, v39, s0
	global_store_short v0, v4, s[6:7] offset:64
	v_cvt_pk_bf16_f32 v4, v40, s0
	global_store_short v0, v4, s[6:7] offset:128
	v_cvt_pk_bf16_f32 v4, v41, s0
	global_store_short v0, v4, s[6:7] offset:192
	v_cvt_pk_bf16_f32 v4, v34, s0
	global_store_short v0, v4, s[6:7] offset:32
	v_cvt_pk_bf16_f32 v4, v35, s0
	global_store_short v0, v4, s[6:7] offset:96
	v_cvt_pk_bf16_f32 v4, v36, s0
	global_store_short v0, v4, s[6:7] offset:160
	v_cvt_pk_bf16_f32 v4, v37, s0
	global_store_short v0, v4, s[6:7] offset:224
	v_cvt_pk_bf16_f32 v4, v30, s0
	global_store_short v2, v4, s[6:7]
	v_cvt_pk_bf16_f32 v4, v31, s0
	global_store_short v2, v4, s[6:7] offset:64
	v_cvt_pk_bf16_f32 v4, v32, s0
	global_store_short v2, v4, s[6:7] offset:128
	v_cvt_pk_bf16_f32 v4, v33, s0
	global_store_short v2, v4, s[6:7] offset:192
	v_cvt_pk_bf16_f32 v4, v26, s0
	global_store_short v2, v4, s[6:7] offset:32
	v_cvt_pk_bf16_f32 v4, v27, s0
	global_store_short v2, v4, s[6:7] offset:96
	v_cvt_pk_bf16_f32 v4, v28, s0
	global_store_short v2, v4, s[6:7] offset:160
	v_cvt_pk_bf16_f32 v4, v29, s0
	global_store_short v2, v4, s[6:7] offset:224

.LBB0_186:
	v_mul_f32_e32 v95, 0x3fb8aa3b, v36
	v_mul_f32_e32 v36, 0xbfb8aa3b, v36
	v_exp_f32_e32 v95, v95
	v_exp_f32_e32 v36, v36
	s_waitcnt vmcnt(55)
	v_lshlrev_b32_e32 v93, 16, v93
	s_waitcnt vmcnt(51)
	v_lshlrev_b32_e32 v94, 16, v94
	s_mul_i32 s6, s35, 0x48
	v_mul_f32_e32 v96, v95, v93
	v_or_b32_e32 v97, s6, v60
	v_mul_f32_e32 v93, v36, v93
	v_mul_f32_e32 v36, v36, v94
	v_lshlrev_b32_e32 v97, 1, v97
	v_cvt_pk_bf16_f32 v36, v36, s0
	ds_write_b16 v97, v36 offset:27648
	v_lshlrev_b32_e32 v36, 16, v91
	v_mul_f32_e32 v91, 0x3fb8aa3b, v37
	v_mul_f32_e32 v37, 0xbfb8aa3b, v37
	v_exp_f32_e32 v91, v91
	v_exp_f32_e32 v37, v37
	v_cvt_pk_bf16_f32 v93, v93, s0
	ds_write_b16 v97, v93 offset:9216
	v_mul_f32_e32 v93, v95, v94
	v_cvt_pk_bf16_f32 v93, v93, s0
	ds_write_b16 v97, v93 offset:18432
	v_mul_f32_e32 v93, v91, v36
	v_mul_f32_e32 v36, v37, v36
	v_cvt_pk_bf16_f32 v96, v96, s0
	s_waitcnt vmcnt(50)
	v_lshlrev_b32_e32 v92, 16, v92
	v_add_lshl_u32 v94, s6, v60, 1
	v_cvt_pk_bf16_f32 v36, v36, s0
	ds_write_b16 v97, v96
	ds_write_b16 v94, v36 offset:9360
	v_mul_f32_e32 v36, v91, v92
	v_cvt_pk_bf16_f32 v36, v36, s0
	ds_write_b16 v94, v36 offset:18576
	v_mul_f32_e32 v36, v37, v92
	v_mul_f32_e32 v37, 0x3fb8aa3b, v34
	v_mul_f32_e32 v34, 0xbfb8aa3b, v34
	v_exp_f32_e32 v37, v37
	v_exp_f32_e32 v34, v34
	v_cvt_pk_bf16_f32 v36, v36, s0
	ds_write_b16 v94, v36 offset:27792
	v_lshlrev_b32_e32 v36, 16, v89
	s_waitcnt vmcnt(49)
	v_lshlrev_b32_e32 v89, 16, v90
	v_mul_f32_e32 v90, v37, v36
	v_mul_f32_e32 v36, v34, v36
	v_cvt_pk_bf16_f32 v36, v36, s0
	ds_write_b16 v94, v36 offset:9504
	v_mul_f32_e32 v36, v37, v89
	v_cvt_pk_bf16_f32 v36, v36, s0
	ds_write_b16 v94, v36 offset:18720
	v_mul_f32_e32 v36, 0x3fb8aa3b, v35
	v_mul_f32_e32 v35, 0xbfb8aa3b, v35
	v_exp_f32_e32 v36, v36
	v_exp_f32_e32 v35, v35
	v_mul_f32_e32 v34, v34, v89
	v_cvt_pk_bf16_f32 v34, v34, s0
	ds_write_b16 v94, v34 offset:27936
	v_lshlrev_b32_e32 v34, 16, v87
	v_mul_f32_e32 v87, v36, v34
	v_mul_f32_e32 v34, v35, v34
	s_waitcnt vmcnt(48)
	v_lshlrev_b32_e32 v37, 16, v88
	v_cvt_pk_bf16_f32 v34, v34, s0
	ds_write_b16 v94, v34 offset:9648
	v_mul_f32_e32 v34, v36, v37
	v_cvt_pk_bf16_f32 v34, v34, s0
	ds_write_b16 v94, v34 offset:18864
	v_mul_f32_e32 v34, v35, v37
	v_mul_f32_e32 v35, 0x3fb8aa3b, v32
	v_mul_f32_e32 v32, 0xbfb8aa3b, v32
	v_exp_f32_e32 v35, v35
	v_exp_f32_e32 v32, v32
	v_cvt_pk_bf16_f32 v34, v34, s0
	ds_write_b16 v94, v34 offset:28080
	s_waitcnt vmcnt(47)
	v_lshlrev_b32_e32 v34, 16, v85
	v_mul_f32_e32 v37, v35, v34
	v_mul_f32_e32 v34, v32, v34
	s_waitcnt vmcnt(44)
	v_lshlrev_b32_e32 v36, 16, v86
	v_cvt_pk_bf16_f32 v34, v34, s0
	ds_write_b16 v94, v34 offset:9792
	v_mul_f32_e32 v34, v35, v36
	v_cvt_pk_bf16_f32 v34, v34, s0
	ds_write_b16 v94, v34 offset:19008
	v_mul_f32_e32 v34, 0x3fb8aa3b, v33
	v_mul_f32_e32 v33, 0xbfb8aa3b, v33
	v_exp_f32_e32 v34, v34
	v_exp_f32_e32 v33, v33
	v_mul_f32_e32 v32, v32, v36
	v_cvt_pk_bf16_f32 v32, v32, s0
	ds_write_b16 v94, v32 offset:28224
	v_lshlrev_b32_e32 v32, 16, v83
	v_mul_f32_e32 v36, v34, v32
	v_mul_f32_e32 v32, v33, v32
	s_waitcnt vmcnt(43)
	v_lshlrev_b32_e32 v35, 16, v84
	v_cvt_pk_bf16_f32 v32, v32, s0
	ds_write_b16 v94, v32 offset:9936
	v_mul_f32_e32 v32, v34, v35
	v_cvt_pk_bf16_f32 v32, v32, s0
	ds_write_b16 v94, v32 offset:19152
	v_mul_f32_e32 v32, v33, v35
	v_mul_f32_e32 v33, 0x3fb8aa3b, v30
	v_mul_f32_e32 v30, 0xbfb8aa3b, v30
	v_exp_f32_e32 v33, v33
	v_exp_f32_e32 v30, v30
	v_cvt_pk_bf16_f32 v32, v32, s0
	ds_write_b16 v94, v32 offset:28368
	v_lshlrev_b32_e32 v32, 16, v80
	v_mul_f32_e32 v35, v33, v32
	v_mul_f32_e32 v32, v30, v32
	s_waitcnt vmcnt(42)
	v_lshlrev_b32_e32 v34, 16, v79
	v_cvt_pk_bf16_f32 v32, v32, s0
	ds_write_b16 v94, v32 offset:10080
	v_mul_f32_e32 v32, v33, v34
	v_cvt_pk_bf16_f32 v32, v32, s0
	ds_write_b16 v94, v32 offset:19296
	v_mul_f32_e32 v32, 0x3fb8aa3b, v31
	v_mul_f32_e32 v31, 0xbfb8aa3b, v31
	v_exp_f32_e32 v32, v32
	v_exp_f32_e32 v31, v31
	v_mul_f32_e32 v30, v30, v34
	v_cvt_pk_bf16_f32 v30, v30, s0
	ds_write_b16 v94, v30 offset:28512
	s_waitcnt vmcnt(39)
	v_lshlrev_b32_e32 v30, 16, v82
	v_mul_f32_e32 v34, v32, v30
	v_mul_f32_e32 v30, v31, v30
	s_waitcnt vmcnt(37)
	v_lshlrev_b32_e32 v33, 16, v81
	v_cvt_pk_bf16_f32 v30, v30, s0
	ds_write_b16 v94, v30 offset:10224
	v_mul_f32_e32 v30, v32, v33
	v_cvt_pk_bf16_f32 v30, v30, s0
	ds_write_b16 v94, v30 offset:19440
	v_mul_f32_e32 v30, v31, v33
	v_mul_f32_e32 v31, 0x3fb8aa3b, v28
	v_mul_f32_e32 v28, 0xbfb8aa3b, v28
	v_exp_f32_e32 v31, v31
	v_exp_f32_e32 v28, v28
	v_cvt_pk_bf16_f32 v30, v30, s0
	ds_write_b16 v94, v30 offset:28656
	v_lshlrev_b32_e32 v30, 16, v78
	v_mul_f32_e32 v33, v31, v30
	v_mul_f32_e32 v30, v28, v30
	v_lshlrev_b32_e32 v32, 16, v77
	v_cvt_pk_bf16_f32 v30, v30, s0
	ds_write_b16 v94, v30 offset:10368
	v_mul_f32_e32 v30, v31, v32
	v_cvt_pk_bf16_f32 v30, v30, s0
	ds_write_b16 v94, v30 offset:19584
	v_mul_f32_e32 v30, 0x3fb8aa3b, v29
	v_mul_f32_e32 v29, 0xbfb8aa3b, v29
	v_exp_f32_e32 v30, v30
	v_exp_f32_e32 v29, v29
	v_mul_f32_e32 v28, v28, v32
	v_cvt_pk_bf16_f32 v28, v28, s0
	ds_write_b16 v94, v28 offset:28800
	v_lshlrev_b32_e32 v28, 16, v76
	v_mul_f32_e32 v32, v30, v28
	v_mul_f32_e32 v28, v29, v28
	s_waitcnt vmcnt(36)
	v_lshlrev_b32_e32 v31, 16, v75
	v_cvt_pk_bf16_f32 v28, v28, s0
	ds_write_b16 v94, v28 offset:10512
	v_mul_f32_e32 v28, v30, v31
	v_cvt_pk_bf16_f32 v28, v28, s0
	ds_write_b16 v94, v28 offset:19728
	v_mul_f32_e32 v28, v29, v31
	v_mul_f32_e32 v29, 0x3fb8aa3b, v26
	v_mul_f32_e32 v26, 0xbfb8aa3b, v26
	v_exp_f32_e32 v29, v29
	v_exp_f32_e32 v26, v26
	v_cvt_pk_bf16_f32 v28, v28, s0
	ds_write_b16 v94, v28 offset:28944
	s_waitcnt vmcnt(35)
	v_lshlrev_b32_e32 v28, 16, v73
	v_mul_f32_e32 v31, v29, v28
	v_mul_f32_e32 v28, v26, v28
	s_waitcnt vmcnt(32)
	v_lshlrev_b32_e32 v30, 16, v74
	v_cvt_pk_bf16_f32 v28, v28, s0
	ds_write_b16 v94, v28 offset:10656
	v_mul_f32_e32 v28, v29, v30
	v_cvt_pk_bf16_f32 v28, v28, s0
	ds_write_b16 v94, v28 offset:19872
	v_mul_f32_e32 v28, 0x3fb8aa3b, v27
	v_mul_f32_e32 v27, 0xbfb8aa3b, v27
	v_exp_f32_e32 v28, v28
	v_exp_f32_e32 v27, v27
	v_mul_f32_e32 v26, v26, v30
	v_cvt_pk_bf16_f32 v26, v26, s0
	ds_write_b16 v94, v26 offset:29088
	v_lshlrev_b32_e32 v26, 16, v71
	v_mul_f32_e32 v30, v28, v26
	v_mul_f32_e32 v26, v27, v26
	s_waitcnt vmcnt(31)
	v_lshlrev_b32_e32 v29, 16, v72
	v_cvt_pk_bf16_f32 v26, v26, s0
	ds_write_b16 v94, v26 offset:10800
	v_mul_f32_e32 v26, v28, v29
	v_cvt_pk_bf16_f32 v26, v26, s0
	ds_write_b16 v94, v26 offset:20016
	v_mul_f32_e32 v26, v27, v29
	v_mul_f32_e32 v27, 0x3fb8aa3b, v24
	v_mul_f32_e32 v24, 0xbfb8aa3b, v24
	v_exp_f32_e32 v27, v27
	v_exp_f32_e32 v24, v24
	v_cvt_pk_bf16_f32 v26, v26, s0
	ds_write_b16 v94, v26 offset:29232
	v_lshlrev_b32_e32 v26, 16, v70
	v_mul_f32_e32 v29, v27, v26
	v_mul_f32_e32 v26, v24, v26
	s_waitcnt vmcnt(30)
	v_lshlrev_b32_e32 v28, 16, v69
	v_cvt_pk_bf16_f32 v26, v26, s0
	ds_write_b16 v94, v26 offset:10944
	v_mul_f32_e32 v26, v27, v28
	v_cvt_pk_bf16_f32 v26, v26, s0
	ds_write_b16 v94, v26 offset:20160
	v_mul_f32_e32 v26, 0x3fb8aa3b, v25
	v_mul_f32_e32 v25, 0xbfb8aa3b, v25
	v_exp_f32_e32 v26, v26
	v_exp_f32_e32 v25, v25
	v_mul_f32_e32 v24, v24, v28
	v_cvt_pk_bf16_f32 v24, v24, s0
	ds_write_b16 v94, v24 offset:29376
	s_waitcnt vmcnt(29)
	v_lshlrev_b32_e32 v24, 16, v67
	v_mul_f32_e32 v28, v26, v24
	v_mul_f32_e32 v24, v25, v24
	s_waitcnt vmcnt(26)
	v_lshlrev_b32_e32 v27, 16, v68
	v_cvt_pk_bf16_f32 v24, v24, s0
	ds_write_b16 v94, v24 offset:11088
	v_mul_f32_e32 v24, v26, v27
	v_cvt_pk_bf16_f32 v24, v24, s0
	ds_write_b16 v94, v24 offset:20304
	v_mul_f32_e32 v24, v25, v27
	v_mul_f32_e32 v25, 0x3fb8aa3b, v22
	v_mul_f32_e32 v22, 0xbfb8aa3b, v22
	v_exp_f32_e32 v25, v25
	v_exp_f32_e32 v22, v22
	v_cvt_pk_bf16_f32 v24, v24, s0
	ds_write_b16 v94, v24 offset:29520
	v_lshlrev_b32_e32 v24, 16, v64
	v_mul_f32_e32 v27, v25, v24
	v_mul_f32_e32 v24, v22, v24
	s_waitcnt vmcnt(25)
	v_lshlrev_b32_e32 v26, 16, v65
	v_cvt_pk_bf16_f32 v24, v24, s0
	ds_write_b16 v94, v24 offset:11232
	v_mul_f32_e32 v24, v25, v26
	v_cvt_pk_bf16_f32 v24, v24, s0
	ds_write_b16 v94, v24 offset:20448
	v_mul_f32_e32 v24, 0x3fb8aa3b, v23
	v_mul_f32_e32 v23, 0xbfb8aa3b, v23
	v_exp_f32_e32 v24, v24
	v_exp_f32_e32 v23, v23
	v_mul_f32_e32 v22, v22, v26
	v_cvt_pk_bf16_f32 v22, v22, s0
	ds_write_b16 v94, v22 offset:29664
	s_or_b32 s6, s36, 15
	v_lshlrev_b32_e32 v22, 16, v63
	v_cvt_pk_bf16_f32 v27, v27, s0
	v_mul_f32_e32 v26, v24, v22
	s_mulk_i32 s6, 0x48
	v_mul_f32_e32 v22, v23, v22
	v_cvt_pk_bf16_f32 v93, v93, s0
	v_cvt_pk_bf16_f32 v90, v90, s0
	v_cvt_pk_bf16_f32 v87, v87, s0
	v_cvt_pk_bf16_f32 v37, v37, s0
	v_cvt_pk_bf16_f32 v36, v36, s0
	v_cvt_pk_bf16_f32 v35, v35, s0
	v_cvt_pk_bf16_f32 v34, v34, s0
	v_cvt_pk_bf16_f32 v33, v33, s0
	v_cvt_pk_bf16_f32 v32, v32, s0
	v_cvt_pk_bf16_f32 v31, v31, s0
	v_cvt_pk_bf16_f32 v30, v30, s0
	v_cvt_pk_bf16_f32 v29, v29, s0
	v_cvt_pk_bf16_f32 v28, v28, s0
	ds_write_b16 v94, v27 offset:2016
	s_waitcnt vmcnt(24)
	v_lshlrev_b32_e32 v25, 16, v62
	v_add_lshl_u32 v27, s6, v60, 1
	v_cvt_pk_bf16_f32 v22, v22, s0
	ds_write_b16 v94, v93 offset:144
	ds_write_b16 v94, v90 offset:288
	ds_write_b16 v94, v87 offset:432
	ds_write_b16 v94, v37 offset:576
	ds_write_b16 v94, v36 offset:720
	ds_write_b16 v94, v35 offset:864
	ds_write_b16 v94, v34 offset:1008
	ds_write_b16 v94, v33 offset:1152
	ds_write_b16 v94, v32 offset:1296
	ds_write_b16 v94, v31 offset:1440
	ds_write_b16 v94, v30 offset:1584
	ds_write_b16 v94, v29 offset:1728
	ds_write_b16 v94, v28 offset:1872
	ds_write_b16 v27, v22 offset:9216
	v_mul_f32_e32 v22, v24, v25
	v_cvt_pk_bf16_f32 v22, v22, s0
	ds_write_b16 v27, v22 offset:18432
	v_mul_f32_e32 v22, v23, v25
	v_mul_lo_u32 v20, v20, s98
	v_cvt_pk_bf16_f32 v26, v26, s0
	v_cvt_pk_bf16_f32 v22, v22, s0
	v_lshl_add_u32 v20, v61, 1, v20
	ds_write_b16 v27, v26
	ds_write_b16 v27, v22 offset:27648
	s_waitcnt vmcnt(23)
	ds_write_b128 v20, v[2:5] offset:36864
	s_waitcnt vmcnt(22)
	ds_write_b128 v20, v[6:9] offset:46080
	s_waitcnt vmcnt(21)
	ds_write_b128 v20, v[10:13] offset:41472
	s_waitcnt vmcnt(20)
	ds_write_b128 v20, v[14:17] offset:50688
	v_lshlrev_b32_e32 v6, 4, v66
	v_mul_u32_u24_e32 v2, 0x48, v54
	v_lshl_add_u32 v20, v2, 1, v6
	s_waitcnt lgkmcnt(0)
	s_barrier
	ds_read_b128 v[2:5], v20 offset:27648
	v_or_b32_e32 v68, s35, v54
	v_mad_u64_u32 v[34:35], s[6:7], v68, s98, v[6:7]
	ds_read_b128 v[6:9], v34
	ds_read_b128 v[10:13], v20 offset:18432
	ds_read_b128 v[22:25], v34 offset:9216
	ds_read_b128 v[26:29], v20 offset:27712
	ds_read_b128 v[14:17], v34 offset:64
	s_waitcnt lgkmcnt(4)
	v_mfma_f32_16x16x32_bf16 v[2:5], v[2:5], v[6:9], 0
	ds_read_b128 v[30:33], v20 offset:18496
	ds_read_b128 v[34:37], v34 offset:9280
	ds_read_b128 v[60:63], v20 offset:30016
	ds_read_b128 v[64:67], v20 offset:20800
	s_waitcnt lgkmcnt(6)
	v_mfma_f32_16x16x32_bf16 v[10:13], v[10:13], v[22:25], 0
	v_cmp_lt_i32_e32 vcc, v68, v59
	s_add_i32 s35, s34, 0x180
	s_and_b64 s[6:7], s[38:39], exec
	s_waitcnt lgkmcnt(4)
	v_mfma_f32_16x16x32_bf16 v[2:5], v[26:29], v[14:17], v[2:5]
	ds_read_b128 v[26:29], v20 offset:29952
	s_cselect_b32 s6, s34, s35
	s_mov_b32 s34, 0x358637bd
	s_waitcnt lgkmcnt(3)
	v_mfma_f32_16x16x32_bf16 v[10:13], v[30:33], v[34:37], v[10:13]
	ds_read_b128 v[30:33], v20 offset:20736
	s_lshr_b32 s6, s6, 5
	s_lshl_b32 s6, s6, 20
	s_add_u32 s6, s48, s6
	s_waitcnt lgkmcnt(1)
	v_mfma_f32_16x16x32_bf16 v[26:29], v[26:29], v[6:9], 0
	s_addc_u32 s7, s49, 0
	s_nop 1
	v_cndmask_b32_e32 v69, v2, v10, vcc
	v_cmp_gt_i32_e32 vcc, v68, v59
	v_or_b32_e32 v2, 2, v59
	s_waitcnt lgkmcnt(0)
	v_mfma_f32_16x16x32_bf16 v[30:33], v[30:33], v[22:25], 0
	v_cndmask_b32_e32 v70, v11, v3, vcc
	v_cmp_lt_i32_e32 vcc, v68, v2
	v_or_b32_e32 v2, 3, v59
	v_mfma_f32_16x16x32_bf16 v[26:29], v[60:63], v[14:17], v[26:29]
	v_cndmask_b32_e32 v71, v4, v12, vcc
	v_cmp_lt_i32_e32 vcc, v68, v2
	ds_read_b128 v[60:63], v20 offset:32256
	s_nop 0
	v_cndmask_b32_e32 v72, v5, v13, vcc
	ds_read_b128 v[10:13], v20 offset:23040
	v_mfma_f32_16x16x32_bf16 v[2:5], v[64:67], v[34:37], v[30:33]
	ds_read_b128 v[64:67], v20 offset:23104
	s_nop 1
	v_or_b32_e32 v30, 16, v59
	v_cmp_lt_i32_e32 vcc, v68, v30
	ds_read_b128 v[30:33], v20 offset:32320
	s_waitcnt lgkmcnt(3)
	v_mfma_f32_16x16x32_bf16 v[60:63], v[60:63], v[6:9], 0
	v_cndmask_b32_e32 v73, v26, v2, vcc
	v_or_b32_e32 v2, 17, v59
	v_cmp_lt_i32_e32 vcc, v68, v2
	s_waitcnt lgkmcnt(2)
	v_mfma_f32_16x16x32_bf16 v[10:13], v[10:13], v[22:25], 0
	v_or_b32_e32 v2, 18, v59
	v_cndmask_b32_e32 v74, v27, v3, vcc
	v_cmp_lt_i32_e32 vcc, v68, v2
	v_or_b32_e32 v2, 19, v59
	s_waitcnt lgkmcnt(0)
	v_mfma_f32_16x16x32_bf16 v[30:33], v[30:33], v[14:17], v[60:63]
	v_cndmask_b32_e32 v75, v28, v4, vcc
	v_cmp_lt_i32_e32 vcc, v68, v2
	v_or_b32_e32 v26, 32, v59
	ds_read_b128 v[60:63], v20 offset:34560
	v_cndmask_b32_e32 v76, v29, v5, vcc
	v_mfma_f32_16x16x32_bf16 v[2:5], v[64:67], v[34:37], v[10:13]
	v_cmp_lt_i32_e32 vcc, v68, v26
	ds_read_b128 v[26:29], v20 offset:34624
	ds_read_b128 v[64:67], v20 offset:25408
	ds_read_b128 v[10:13], v20 offset:25344
	s_waitcnt lgkmcnt(3)
	v_mfma_f32_16x16x32_bf16 v[60:63], v[60:63], v[6:9], 0
	s_nop 1
	v_cndmask_b32_e32 v77, v30, v2, vcc
	v_or_b32_e32 v2, 33, v59
	v_cmp_lt_i32_e32 vcc, v68, v2
	s_waitcnt lgkmcnt(0)
	v_mfma_f32_16x16x32_bf16 v[10:13], v[10:13], v[22:25], 0
	v_or_b32_e32 v2, 34, v59
	v_cndmask_b32_e32 v78, v31, v3, vcc
	v_cmp_lt_i32_e32 vcc, v68, v2
	v_or_b32_e32 v2, 35, v59
	v_mfma_f32_16x16x32_bf16 v[22:25], v[26:29], v[14:17], v[60:63]
	v_cndmask_b32_e32 v20, v32, v4, vcc
	v_cmp_lt_i32_e32 vcc, v68, v2
	v_lshlrev_b32_e32 v26, 1, v59
	v_or_b32_e32 v30, 48, v59
	v_cndmask_b32_e32 v79, v33, v5, vcc
	v_mfma_f32_16x16x32_bf16 v[2:5], v[64:67], v[34:37], v[10:13]
	v_mad_u32_u24 v60, v54, s98, v26
	v_add_u32_e32 v64, 0x9000, v60
	v_cmp_lt_i32_e32 vcc, v68, v30
	v_add_u32_e32 v65, 0x9800, v60
	v_add_u32_e32 v66, 0xa000, v60
	v_add_u32_e32 v67, 0xa800, v60
	v_cvt_pk_bf16_f32 v10, v69, v70
	v_cvt_pk_bf16_f32 v11, v71, v72
	v_cvt_pk_bf16_f32 v12, v73, v74
	v_cvt_pk_bf16_f32 v13, v75, v76
	ds_read2_b64 v[26:29], v64 offset1:4
	v_cndmask_b32_e32 v22, v22, v2, vcc
	v_or_b32_e32 v2, 49, v59
	ds_read2_b64 v[30:33], v65 offset0:32 offset1:36
	ds_read2_b64 v[34:37], v66 offset0:64 offset1:68
	ds_read2_b64 v[60:63], v67 offset0:96 offset1:100
	v_cmp_lt_i32_e32 vcc, v68, v2
	v_or_b32_e32 v2, 50, v59
	s_waitcnt lgkmcnt(3)
	v_mfma_f32_16x16x32_bf16 v[26:29], v[10:13], v[26:29], 0
	v_cndmask_b32_e32 v23, v23, v3, vcc
	v_cmp_lt_i32_e32 vcc, v68, v2
	v_or_b32_e32 v2, 51, v59
	s_waitcnt lgkmcnt(2)
	v_mfma_f32_16x16x32_bf16 v[30:33], v[10:13], v[30:33], 0
	v_cndmask_b32_e32 v24, v24, v4, vcc
	v_cmp_lt_i32_e32 vcc, v68, v2
	s_waitcnt lgkmcnt(1)
	v_mfma_f32_16x16x32_bf16 v[34:37], v[10:13], v[34:37], 0
	v_cndmask_b32_e32 v25, v25, v5, vcc
	s_waitcnt lgkmcnt(0)
	v_mfma_f32_16x16x32_bf16 v[2:5], v[10:13], v[60:63], 0
	v_cvt_pk_bf16_f32 v10, v77, v78
	v_cvt_pk_bf16_f32 v11, v20, v79
	v_cvt_pk_bf16_f32 v12, v22, v23
	v_cvt_pk_bf16_f32 v13, v24, v25
	ds_read2_b64 v[22:25], v64 offset0:8 offset1:12
	s_waitcnt lgkmcnt(0)
	v_mfma_f32_16x16x32_bf16 v[22:25], v[10:13], v[22:25], v[26:29]
	s_nop 2
	ds_read2_b64 v[26:29], v65 offset0:40 offset1:44
	s_waitcnt lgkmcnt(0)
	v_mfma_f32_16x16x32_bf16 v[26:29], v[10:13], v[26:29], v[30:33]
	s_nop 2
	ds_read2_b64 v[30:33], v66 offset0:72 offset1:76
	s_waitcnt lgkmcnt(0)
	v_mfma_f32_16x16x32_bf16 v[30:33], v[10:13], v[30:33], v[34:37]
	s_nop 2
	ds_read2_b64 v[34:37], v67 offset0:104 offset1:108
	s_waitcnt lgkmcnt(0)
	v_mfma_f32_16x16x32_bf16 v[2:5], v[10:13], v[34:37], v[2:5]
	v_and_b32_e32 v10, 48, v53
	v_mad_u32_u24 v20, v54, s98, v10
	ds_read_b128 v[10:13], v20 offset:46080
	s_waitcnt lgkmcnt(0)
	v_mfma_f32_16x16x32_bf16 v[10:13], v[6:9], v[10:13], v[22:25]
	s_nop 2
	ds_read_b128 v[22:25], v20 offset:48384
	s_waitcnt lgkmcnt(0)
	v_mfma_f32_16x16x32_bf16 v[22:25], v[6:9], v[22:25], v[26:29]
	s_nop 2
	ds_read_b128 v[26:29], v20 offset:50688
	s_waitcnt lgkmcnt(0)
	v_mfma_f32_16x16x32_bf16 v[26:29], v[6:9], v[26:29], v[30:33]
	s_nop 2
	ds_read_b128 v[30:33], v20 offset:52992
	s_waitcnt lgkmcnt(0)
	v_mfma_f32_16x16x32_bf16 v[30:33], v[6:9], v[30:33], v[2:5]
	ds_read_b128 v[6:9], v20 offset:48448
	s_nop 1
	ds_read_b128 v[2:5], v20 offset:46144
	s_waitcnt lgkmcnt(0)
	v_mfma_f32_16x16x32_bf16 v[2:5], v[14:17], v[2:5], v[10:13]
	s_nop 2
	ds_read_b128 v[10:13], v20 offset:50752
	v_mfma_f32_16x16x32_bf16 v[6:9], v[14:17], v[6:9], v[22:25]
	s_nop 2
	ds_read_b128 v[22:25], v20 offset:53056
	s_waitcnt lgkmcnt(1)
	v_mfma_f32_16x16x32_bf16 v[10:13], v[14:17], v[10:13], v[26:29]
	v_and_b32_e32 v20, 64, v159
	v_add_u32_e32 v20, 64, v20
	s_waitcnt lgkmcnt(0)
	v_mfma_f32_16x16x32_bf16 v[14:17], v[14:17], v[22:25], v[30:33]
	v_mov_b32_e32 v22, v2
	s_nop 2
	v_mov_b32_e32 v23, v10
	v_mov_b32_e32 v24, v6
	v_xor_b32_e32 v27, 1, v159
	s_nop 0
	v_mov_b32_e32 v25, v14
	v_pk_add_f32 v[22:23], v[22:23], v[24:25]
	s_nop 0
	v_add_f32_e32 v22, v22, v23
	v_xor_b32_e32 v23, 8, v159
	v_cmp_lt_i32_e32 vcc, v23, v20
	s_nop 1
	v_cndmask_b32_e32 v23, v159, v23, vcc
	v_lshlrev_b32_e32 v32, 2, v23
	ds_bpermute_b32 v23, v32, v22
	s_waitcnt lgkmcnt(0)
	v_add_f32_e32 v22, v22, v23
	v_xor_b32_e32 v23, 4, v159
	v_cmp_lt_i32_e32 vcc, v23, v20
	s_nop 1
	v_cndmask_b32_e32 v23, v159, v23, vcc
	v_lshlrev_b32_e32 v33, 2, v23
	ds_bpermute_b32 v23, v33, v22
	s_waitcnt lgkmcnt(0)
	v_add_f32_e32 v22, v22, v23
	v_xor_b32_e32 v23, 2, v159
	v_cmp_lt_i32_e32 vcc, v23, v20
	s_nop 1
	v_cndmask_b32_e32 v23, v159, v23, vcc
	v_lshlrev_b32_e32 v34, 2, v23
	ds_bpermute_b32 v23, v34, v22
	v_cmp_lt_i32_e32 vcc, v27, v20
	s_waitcnt lgkmcnt(0)
	v_add_f32_e32 v26, v22, v23
	v_mov_b32_e32 v22, v14
	v_mov_b32_e32 v23, v10
	v_mov_b32_e32 v10, v3
	v_mov_b32_e32 v14, v7
	v_pk_add_f32 v[24:25], v[10:11], v[14:15]
	v_cndmask_b32_e32 v20, v159, v27, vcc
	v_add_f32_e32 v10, v24, v25
	ds_bpermute_b32 v14, v32, v10
	v_lshlrev_b32_e32 v20, 2, v20
	ds_bpermute_b32 v24, v20, v26
	v_mov_b32_e32 v25, v6
	s_waitcnt lgkmcnt(1)
	v_add_f32_e32 v10, v10, v14
	ds_bpermute_b32 v14, v33, v10
	s_waitcnt lgkmcnt(1)
	v_add_f32_e32 v24, v26, v24
	s_waitcnt lgkmcnt(0)
	v_add_f32_e32 v14, v10, v14
	ds_bpermute_b32 v26, v34, v14
	v_mul_f32_e32 v10, 0x3c800000, v24
	v_mov_b32_e32 v24, v2
	v_cndmask_b32_e64 v10, 0, v10, s[38:39]
	v_pk_add_f32 v[24:25], v[24:25], v[10:11] op_sel_hi:[1,0] neg_lo:[0,1] neg_hi:[0,1]
	s_waitcnt lgkmcnt(0)
	v_add_f32_e32 v2, v14, v26
	ds_bpermute_b32 v6, v20, v2
	v_pk_add_f32 v[22:23], v[22:23], v[10:11] op_sel_hi:[1,0] neg_lo:[0,1] neg_hi:[0,1]
	v_mov_b32_e32 v10, v15
	v_pk_mul_f32 v[26:27], v[24:25], v[24:25]
	v_pk_mul_f32 v[28:29], v[22:23], v[22:23]
	s_waitcnt lgkmcnt(0)
	v_add_f32_e32 v2, v2, v6
	v_mul_f32_e32 v2, 0x3c800000, v2
	v_cndmask_b32_e64 v2, 0, v2, s[38:39]
	v_mov_b32_e32 v6, v3
	v_pk_add_f32 v[6:7], v[6:7], v[2:3] op_sel_hi:[1,0] neg_lo:[0,1] neg_hi:[0,1]
	v_pk_add_f32 v[10:11], v[10:11], v[2:3] op_sel_hi:[1,0] neg_lo:[0,1] neg_hi:[0,1]
	v_pk_mul_f32 v[30:31], v[6:7], v[6:7]
	v_pk_mul_f32 v[2:3], v[10:11], v[10:11]
	v_mov_b32_e32 v14, v30
	v_mov_b32_e32 v15, v26
	v_mov_b32_e32 v26, v31
	v_pk_add_f32 v[14:15], v[14:15], v[26:27]
	v_mov_b32_e32 v26, v3
	v_mov_b32_e32 v27, v29
	v_pk_add_f32 v[14:15], v[26:27], v[14:15]
	v_mov_b32_e32 v3, v28
	v_pk_add_f32 v[2:3], v[2:3], v[14:15]
	ds_bpermute_b32 v15, v32, v3
	ds_bpermute_b32 v14, v32, v2
	s_waitcnt vmcnt(15)
	v_lshlrev_b32_e32 v28, 16, v58
	s_waitcnt vmcnt(11)
	v_lshlrev_b32_e32 v30, 16, v56
	s_waitcnt vmcnt(8)
	v_lshlrev_b32_e32 v31, 16, v57
	s_waitcnt lgkmcnt(0)
	v_pk_add_f32 v[2:3], v[2:3], v[14:15]
	ds_bpermute_b32 v15, v33, v3
	ds_bpermute_b32 v14, v33, v2
	s_waitcnt lgkmcnt(0)
	v_pk_add_f32 v[2:3], v[2:3], v[14:15]
	ds_bpermute_b32 v15, v34, v3
	ds_bpermute_b32 v14, v34, v2
	s_waitcnt lgkmcnt(0)
	v_pk_add_f32 v[14:15], v[2:3], v[14:15]
	ds_bpermute_b32 v27, v20, v15
	ds_bpermute_b32 v26, v20, v14
	v_lshl_add_u32 v245, v18, 6, v0
	v_add_u32_e32 v246, 0x100000, v245
	s_waitcnt lgkmcnt(0)
	v_pk_add_f32 v[14:15], v[14:15], v[26:27]
	v_mov_b64_e32 v[26:27], s[34:35]
	s_mov_b32 s34, 0x3c800000
	v_pk_fma_f32 v[14:15], v[14:15], s[34:35], v[26:27] op_sel_hi:[1,0,0]
	s_nop 0
	v_mul_f32_e32 v29, 0x4b800000, v15
	v_cmp_gt_f32_e32 vcc, s84, v15
	s_nop 1
	v_cndmask_b32_e32 v15, v15, v29, vcc
	v_rsq_f32_e32 v15, v15
	v_lshlrev_b32_e32 v29, 16, v55
	v_mul_f32_e32 v35, 0x45800000, v15
	v_cndmask_b32_e32 v15, v15, v35, vcc
	v_mul_f32_e32 v24, v24, v15
	v_mul_f32_e32 v24, v40, v24
	v_mul_f32_e32 v24, v24, v28
	v_cvt_pk_bf16_f32 v24, v24, s0
	global_store_short v245, v24, s[6:7]
	v_mul_f32_e32 v24, v25, v15
	v_mul_f32_e32 v23, v23, v15
	v_mul_f32_e32 v15, v22, v15
	v_mul_f32_e32 v24, v39, v24
	v_mul_f32_e32 v23, v38, v23
	v_mul_f32_e32 v15, v21, v15
	v_mul_f32_e32 v24, v24, v29
	v_mul_f32_e32 v23, v23, v30
	v_mul_f32_e32 v15, v15, v31
	v_cvt_pk_bf16_f32 v24, v24, s0
	v_cvt_pk_bf16_f32 v23, v23, s0
	v_mul_f32_e32 v22, 0x4b800000, v14
	v_cmp_gt_f32_e32 vcc, s84, v14
	v_cvt_pk_bf16_f32 v15, v15, s0
	global_store_short v245, v24, s[6:7] offset:32
	global_store_short v246, v23, s[6:7]
	v_cndmask_b32_e32 v14, v14, v22, vcc
	global_store_short v246, v15, s[6:7] offset:32
	v_mov_b32_e32 v18, v4
	v_mov_b32_e32 v19, v12
	v_mov_b32_e32 v22, v8
	v_mov_b32_e32 v23, v16
	v_pk_add_f32 v[18:19], v[18:19], v[22:23]
	v_rsq_f32_e32 v14, v14
	v_add_f32_e32 v18, v18, v19
	ds_bpermute_b32 v19, v32, v18
	v_lshlrev_b32_e32 v24, 16, v52
	v_mul_f32_e32 v15, 0x45800000, v14
	v_cndmask_b32_e32 v30, v14, v15, vcc
	v_mul_f32_e32 v6, v6, v30
	s_waitcnt lgkmcnt(0)
	v_add_f32_e32 v18, v18, v19
	ds_bpermute_b32 v19, v33, v18
	v_mul_f32_e32 v6, v40, v6
	v_mul_f32_e32 v6, v6, v24
	v_cvt_pk_bf16_f32 v6, v6, s0
	global_store_short v245, v6, s[6:7] offset:64
	v_mul_f32_e32 v23, v7, v30
	v_mov_b32_e32 v6, v16
	v_mov_b32_e32 v7, v12
	v_mov_b32_e32 v12, v5
	v_mov_b32_e32 v16, v9
	s_waitcnt lgkmcnt(0)
	v_add_f32_e32 v24, v18, v19
	v_pk_add_f32 v[18:19], v[12:13], v[16:17]
	ds_bpermute_b32 v25, v34, v24
	v_add_f32_e32 v12, v18, v19
	ds_bpermute_b32 v16, v32, v12
	v_lshlrev_b32_e32 v22, 16, v51
	v_mul_f32_e32 v18, v39, v23
	s_waitcnt lgkmcnt(1)
	v_add_f32_e32 v19, v24, v25
	v_mul_f32_e32 v18, v18, v22
	s_waitcnt lgkmcnt(0)
	v_add_f32_e32 v12, v12, v16
	ds_bpermute_b32 v16, v33, v12
	ds_bpermute_b32 v22, v20, v19
	v_cvt_pk_bf16_f32 v18, v18, s0
	global_store_short v245, v18, s[6:7] offset:96
	v_mul_f32_e32 v11, v11, v30
	s_waitcnt lgkmcnt(1)
	v_add_f32_e32 v16, v12, v16
	s_waitcnt lgkmcnt(0)
	v_add_f32_e32 v18, v19, v22
	ds_bpermute_b32 v22, v34, v16
	v_mul_f32_e32 v12, 0x3c800000, v18
	v_mov_b32_e32 v18, v4
	v_mov_b32_e32 v19, v8
	v_cndmask_b32_e64 v12, 0, v12, s[38:39]
	s_waitcnt lgkmcnt(0)
	v_add_f32_e32 v4, v16, v22
	ds_bpermute_b32 v8, v20, v4
	v_pk_add_f32 v[18:19], v[18:19], v[12:13] op_sel_hi:[1,0] neg_lo:[0,1] neg_hi:[0,1]
	v_pk_add_f32 v[6:7], v[6:7], v[12:13] op_sel_hi:[1,0] neg_lo:[0,1] neg_hi:[0,1]
	v_mov_b32_e32 v12, v17
	v_pk_mul_f32 v[22:23], v[18:19], v[18:19]
	s_waitcnt lgkmcnt(0)
	v_add_f32_e32 v4, v4, v8
	v_mul_f32_e32 v4, 0x3c800000, v4
	v_cndmask_b32_e64 v4, 0, v4, s[38:39]
	v_mov_b32_e32 v8, v5
	v_pk_add_f32 v[8:9], v[8:9], v[4:5] op_sel_hi:[1,0] neg_lo:[0,1] neg_hi:[0,1]
	v_pk_add_f32 v[4:5], v[12:13], v[4:5] op_sel_hi:[1,0] neg_lo:[0,1] neg_hi:[0,1]
	v_pk_mul_f32 v[28:29], v[8:9], v[8:9]
	v_pk_mul_f32 v[24:25], v[6:7], v[6:7]
	v_pk_mul_f32 v[12:13], v[4:5], v[4:5]
	v_mov_b32_e32 v16, v28
	v_mov_b32_e32 v17, v22
	v_mov_b32_e32 v22, v29
	v_pk_add_f32 v[16:17], v[16:17], v[22:23]
	v_mov_b32_e32 v22, v13
	v_mov_b32_e32 v23, v25
	v_pk_add_f32 v[16:17], v[22:23], v[16:17]
	v_mov_b32_e32 v13, v24
	v_pk_add_f32 v[12:13], v[12:13], v[16:17]
	ds_bpermute_b32 v17, v32, v13
	ds_bpermute_b32 v16, v32, v12
	v_lshlrev_b32_e32 v31, 16, v50
	v_mul_f32_e32 v11, v38, v11
	v_mul_f32_e32 v11, v11, v31
	v_cvt_pk_bf16_f32 v11, v11, s0
	s_waitcnt lgkmcnt(0)
	v_pk_add_f32 v[12:13], v[12:13], v[16:17]
	ds_bpermute_b32 v17, v33, v13
	ds_bpermute_b32 v16, v33, v12
	v_mul_f32_e32 v10, v10, v30
	global_store_short v246, v11, s[6:7] offset:64
	v_mul_f32_e32 v23, v21, v10
	v_lshlrev_b32_e32 v22, 16, v49
	s_waitcnt lgkmcnt(0)
	v_pk_add_f32 v[10:11], v[12:13], v[16:17]
	ds_bpermute_b32 v13, v34, v11
	ds_bpermute_b32 v12, v34, v10
	v_mul_f32_e32 v16, v23, v22
	v_cvt_pk_bf16_f32 v16, v16, s0
	global_store_short v246, v16, s[6:7] offset:96
	s_waitcnt lgkmcnt(0)
	v_pk_add_f32 v[10:11], v[10:11], v[12:13]
	ds_bpermute_b32 v13, v20, v11
	ds_bpermute_b32 v12, v20, v10
	s_waitcnt vmcnt(8)
	v_lshlrev_b32_e32 v17, 16, v47
	s_waitcnt lgkmcnt(0)
	v_pk_add_f32 v[10:11], v[10:11], v[12:13]
	v_lshlrev_b32_e32 v13, 16, v46
	v_pk_fma_f32 v[10:11], v[10:11], s[34:35], v[26:27] op_sel_hi:[1,0,0]
	v_mul_f32_e32 v12, 0x4b800000, v11
	v_cmp_gt_f32_e32 vcc, s84, v11
	v_cndmask_b32_e32 v11, v11, v12, vcc
	v_rsq_f32_e32 v11, v11
	v_lshlrev_b32_e32 v0, 16, v43
	v_lshlrev_b32_e32 v16, 16, v48
	v_lshlrev_b32_e32 v12, 16, v45
	v_mul_f32_e32 v20, 0x45800000, v11
	v_cndmask_b32_e32 v11, v11, v20, vcc
	v_mul_f32_e32 v7, v7, v11
	v_mul_f32_e32 v7, v38, v7
	v_mul_f32_e32 v7, v7, v13
	v_cvt_pk_bf16_f32 v7, v7, s0
	global_store_short v246, v7, s[6:7] offset:128
	v_mul_f32_e32 v7, 0x4b800000, v10
	v_cmp_gt_f32_e32 vcc, s84, v10
	v_mul_f32_e32 v6, v6, v11
	v_mul_f32_e32 v6, v21, v6
	v_cndmask_b32_e32 v7, v10, v7, vcc
	v_rsq_f32_e32 v7, v7
	v_mul_f32_e32 v6, v6, v17
	v_cvt_pk_bf16_f32 v6, v6, s0
	global_store_short v246, v6, s[6:7] offset:160
	v_mul_f32_e32 v6, 0x45800000, v7
	v_cndmask_b32_e32 v6, v7, v6, vcc
	v_mul_f32_e32 v8, v8, v6
	v_lshlrev_b32_e32 v7, 16, v44
	v_mul_f32_e32 v8, v40, v8
	v_mul_f32_e32 v7, v8, v7
	v_cvt_pk_bf16_f32 v7, v7, s0
	global_store_short v245, v7, s[6:7] offset:192
	v_mul_f32_e32 v7, v9, v6
	v_mul_f32_e32 v7, v39, v7
	v_mul_f32_e32 v18, v18, v11
	v_mul_f32_e32 v0, v7, v0
	v_mul_f32_e32 v18, v40, v18
	v_cvt_pk_bf16_f32 v0, v0, s0
	v_mul_f32_e32 v5, v5, v6
	v_mul_f32_e32 v16, v18, v16
	global_store_short v245, v0, s[6:7] offset:224
	v_lshlrev_b32_e32 v0, 16, v42
	v_mul_f32_e32 v5, v38, v5
	v_cvt_pk_bf16_f32 v16, v16, s0
	v_mul_f32_e32 v0, v5, v0
	global_store_short v245, v16, s[6:7] offset:128
	v_mul_f32_e32 v16, v19, v11
	v_cvt_pk_bf16_f32 v0, v0, s0
	v_mul_f32_e32 v4, v4, v6
	v_mul_f32_e32 v16, v39, v16
	global_store_short v246, v0, s[6:7] offset:192
	v_lshlrev_b32_e32 v0, 16, v41
	v_mul_f32_e32 v4, v21, v4
	v_mul_f32_e32 v12, v16, v12
	v_mul_f32_e32 v0, v4, v0
	v_cvt_pk_bf16_f32 v12, v12, s0
	v_cvt_pk_bf16_f32 v0, v0, s0
	global_store_short v245, v12, s[6:7] offset:160
	global_store_short v246, v0, s[6:7] offset:224
	s_branch .LBB0_180

.Lcv_m1a:
	s_cmpk_lt_u32 s26, 0x980
	s_cbranch_scc0 .Lcv_m2a
	s_add_i32 s37, s26, 0xfffff880
	s_lshr_b32 s34, s37, 4
	s_and_b32 s35, s37, 15
	s_mov_b64 s[38:39], s[56:57]
	s_mov_b64 s[40:41], s[96:97]
	s_mov_b32 s43, 0x400000
	s_movk_i32 s36, 0x1000
	s_mov_b32 s37, 0x10000
	s_movk_i32 s32, 1
	s_branch .Lcv_deca

.Lcv_deca:
	s_mul_i32 s37, s37, s34
	s_cmp_eq_u32 s32, 1
	s_cselect_b32 s42, 64, 64
	s_lshl_b32 s53, s35, 6
	s_mul_i32 s53, s53, s42
	s_add_i32 s37, s37, s53
	v_mul_lo_u32 v48, v34, s42
	s_add_u32 s40, s40, s37
	s_addc_u32 s41, s41, 0
	s_mul_i32 s43, s43, s28
	s_lshl_b32 s52, s34, 5
	s_mul_i32 s52, s52, s36
	s_add_u32 s43, s43, s52
	s_add_u32 s38, s38, s43
	s_addc_u32 s39, s39, 0
	v_lshlrev_b32_e32 v37, 2, v36
	s_cmp_eq_u32 s32, 2
	s_cbranch_scc1 .Lcv_upa
	s_lshl_b32 s52, s35, 6
	v_add_u32_e32 v37, s52, v37
	s_branch .Lcv_cola

.Lgy_kdone:
	s_cmp_eq_u32 s37, 0
	s_cbranch_scc1 .Lgy_tail_last
	s_waitcnt vmcnt(6) lgkmcnt(0)
	s_barrier
	v_add_u32_e32 v240, s61, v238
	v_add_u32_e32 v241, s61, v239
	s_add_i32 m0, s60, s62
	v_mfma_f32_16x16x32_bf16 v[2:5], v[162:165], v[130:133], v[2:5]
	global_load_lds_dwordx4 v226, s[54:55]
	v_mfma_f32_16x16x32_bf16 v[6:9], v[166:169], v[130:133], v[6:9]
	global_load_lds_dwordx4 v226, s[54:55] offset:1024
	v_mfma_f32_16x16x32_bf16 v[10:13], v[170:173], v[130:133], v[10:13]
	global_load_lds_dwordx4 v226, s[54:55] offset:2048
	v_mfma_f32_16x16x32_bf16 v[14:17], v[174:177], v[130:133], v[14:17]
	global_load_lds_dwordx4 v226, s[54:55] offset:3072
	s_add_i32 m0, s60, s63
	v_mfma_f32_16x16x32_bf16 v[18:21], v[162:165], v[134:137], v[18:21]
	global_load_lds_dwordx4 v230, s[56:57]
	v_mfma_f32_16x16x32_bf16 v[22:25], v[166:169], v[134:137], v[22:25]
	global_load_lds_dwordx4 v231, s[56:57] offset:1024
	v_mfma_f32_16x16x32_bf16 v[26:29], v[170:173], v[134:137], v[26:29]
	v_mfma_f32_16x16x32_bf16 v[30:33], v[174:177], v[134:137], v[30:33]
	v_mfma_f32_16x16x32_bf16 v[34:37], v[162:165], v[138:141], v[34:37]
	ds_read_b128 v[210:213], v241 offset:0
	v_mfma_f32_16x16x32_bf16 v[38:41], v[166:169], v[138:141], v[38:41]
	ds_read_b128 v[214:217], v241 offset:256
	v_mfma_f32_16x16x32_bf16 v[42:45], v[170:173], v[138:141], v[42:45]
	ds_read_b128 v[218:221], v241 offset:512
	v_mfma_f32_16x16x32_bf16 v[46:49], v[174:177], v[138:141], v[46:49]
	ds_read_b128 v[222:225], v241 offset:768
	v_mfma_f32_16x16x32_bf16 v[50:53], v[162:165], v[142:145], v[50:53]
	ds_read_b128 v[178:181], v240 offset:0
	v_mfma_f32_16x16x32_bf16 v[54:57], v[166:169], v[142:145], v[54:57]
	ds_read_b128 v[182:185], v240 offset:1024
	v_mfma_f32_16x16x32_bf16 v[58:61], v[170:173], v[142:145], v[58:61]
	ds_read_b128 v[186:189], v240 offset:2048
	v_mfma_f32_16x16x32_bf16 v[62:65], v[174:177], v[142:145], v[62:65]
	ds_read_b128 v[190:193], v240 offset:3072
	v_mfma_f32_16x16x32_bf16 v[66:69], v[162:165], v[146:149], v[66:69]
	ds_read_b128 v[194:197], v240 offset:4096
	v_mfma_f32_16x16x32_bf16 v[70:73], v[166:169], v[146:149], v[70:73]
	ds_read_b128 v[198:201], v240 offset:5120
	v_mfma_f32_16x16x32_bf16 v[74:77], v[170:173], v[146:149], v[74:77]
	ds_read_b128 v[202:205], v240 offset:6144
	v_mfma_f32_16x16x32_bf16 v[78:81], v[174:177], v[146:149], v[78:81]
	ds_read_b128 v[206:209], v240 offset:7168
	s_setprio 1
	v_mfma_f32_16x16x32_bf16 v[82:85], v[162:165], v[150:153], v[82:85]
	v_mfma_f32_16x16x32_bf16 v[86:89], v[166:169], v[150:153], v[86:89]
	v_mfma_f32_16x16x32_bf16 v[90:93], v[170:173], v[150:153], v[90:93]
	v_mfma_f32_16x16x32_bf16 v[94:97], v[174:177], v[150:153], v[94:97]
	v_mfma_f32_16x16x32_bf16 v[98:101], v[162:165], v[154:157], v[98:101]
	v_mfma_f32_16x16x32_bf16 v[102:105], v[166:169], v[154:157], v[102:105]
	v_mfma_f32_16x16x32_bf16 v[106:109], v[170:173], v[154:157], v[106:109]
	v_mfma_f32_16x16x32_bf16 v[110:113], v[174:177], v[154:157], v[110:113]
	v_mfma_f32_16x16x32_bf16 v[114:117], v[162:165], v[158:161], v[114:117]
	v_mfma_f32_16x16x32_bf16 v[118:121], v[166:169], v[158:161], v[118:121]
	v_mfma_f32_16x16x32_bf16 v[122:125], v[170:173], v[158:161], v[122:125]
	v_mfma_f32_16x16x32_bf16 v[126:129], v[174:177], v[158:161], v[126:129]
	s_setprio 0
	s_add_i32 s60, s60, 0x6000
	s_cmp_eq_u32 s60, 0x12000
	s_cselect_b32 s60, 0, s60
	s_add_u32 s54, s54, s72
	s_addc_u32 s55, s55, 0
	s_add_u32 s56, s56, s73
	s_addc_u32 s57, s57, 0
	s_add_i32 s61, s61, 0x6000
	s_cmp_eq_u32 s61, 0x12000
	s_cselect_b32 s61, 0, s61
	v_mov_b32_e32 v226, v232
	v_mov_b32_e32 v230, v236
	v_mov_b32_e32 v231, v237
	s_mov_b64 s[54:55], s[48:49]
	s_mov_b64 s[56:57], s[50:51]
	s_waitcnt vmcnt(6) lgkmcnt(0)
	s_barrier
	v_add_u32_e32 v240, s61, v238
	v_add_u32_e32 v241, s61, v239
	s_add_i32 m0, s60, s62
	v_mfma_f32_16x16x32_bf16 v[2:5], v[210:213], v[178:181], v[2:5]
	global_load_lds_dwordx4 v226, s[54:55]
	v_mfma_f32_16x16x32_bf16 v[6:9], v[214:217], v[178:181], v[6:9]
	global_load_lds_dwordx4 v226, s[54:55] offset:1024
	v_mfma_f32_16x16x32_bf16 v[10:13], v[218:221], v[178:181], v[10:13]
	global_load_lds_dwordx4 v226, s[54:55] offset:2048
	v_mfma_f32_16x16x32_bf16 v[14:17], v[222:225], v[178:181], v[14:17]
	global_load_lds_dwordx4 v226, s[54:55] offset:3072
	s_add_i32 m0, s60, s63
	v_mfma_f32_16x16x32_bf16 v[18:21], v[210:213], v[182:185], v[18:21]
	global_load_lds_dwordx4 v230, s[56:57]
	v_mfma_f32_16x16x32_bf16 v[22:25], v[214:217], v[182:185], v[22:25]
	global_load_lds_dwordx4 v231, s[56:57] offset:1024
	v_mfma_f32_16x16x32_bf16 v[26:29], v[218:221], v[182:185], v[26:29]
	v_mfma_f32_16x16x32_bf16 v[30:33], v[222:225], v[182:185], v[30:33]
	v_mfma_f32_16x16x32_bf16 v[34:37], v[210:213], v[186:189], v[34:37]
	ds_read_b128 v[162:165], v241 offset:0
	v_mfma_f32_16x16x32_bf16 v[38:41], v[214:217], v[186:189], v[38:41]
	ds_read_b128 v[166:169], v241 offset:256
	v_mfma_f32_16x16x32_bf16 v[42:45], v[218:221], v[186:189], v[42:45]
	ds_read_b128 v[170:173], v241 offset:512
	v_mfma_f32_16x16x32_bf16 v[46:49], v[222:225], v[186:189], v[46:49]
	ds_read_b128 v[174:177], v241 offset:768
	v_mfma_f32_16x16x32_bf16 v[50:53], v[210:213], v[190:193], v[50:53]
	ds_read_b128 v[130:133], v240 offset:0
	v_mfma_f32_16x16x32_bf16 v[54:57], v[214:217], v[190:193], v[54:57]
	ds_read_b128 v[134:137], v240 offset:1024
	v_mfma_f32_16x16x32_bf16 v[58:61], v[218:221], v[190:193], v[58:61]
	ds_read_b128 v[138:141], v240 offset:2048
	v_mfma_f32_16x16x32_bf16 v[62:65], v[222:225], v[190:193], v[62:65]
	ds_read_b128 v[142:145], v240 offset:3072
	v_mfma_f32_16x16x32_bf16 v[66:69], v[210:213], v[194:197], v[66:69]
	ds_read_b128 v[146:149], v240 offset:4096
	v_mfma_f32_16x16x32_bf16 v[70:73], v[214:217], v[194:197], v[70:73]
	ds_read_b128 v[150:153], v240 offset:5120
	v_mfma_f32_16x16x32_bf16 v[74:77], v[218:221], v[194:197], v[74:77]
	ds_read_b128 v[154:157], v240 offset:6144
	v_mfma_f32_16x16x32_bf16 v[78:81], v[222:225], v[194:197], v[78:81]
	ds_read_b128 v[158:161], v240 offset:7168
	s_setprio 1
	v_mfma_f32_16x16x32_bf16 v[82:85], v[210:213], v[198:201], v[82:85]
	v_mfma_f32_16x16x32_bf16 v[86:89], v[214:217], v[198:201], v[86:89]
	v_mfma_f32_16x16x32_bf16 v[90:93], v[218:221], v[198:201], v[90:93]
	v_mfma_f32_16x16x32_bf16 v[94:97], v[222:225], v[198:201], v[94:97]
	v_mfma_f32_16x16x32_bf16 v[98:101], v[210:213], v[202:205], v[98:101]
	v_mfma_f32_16x16x32_bf16 v[102:105], v[214:217], v[202:205], v[102:105]
	v_mfma_f32_16x16x32_bf16 v[106:109], v[218:221], v[202:205], v[106:109]
	v_mfma_f32_16x16x32_bf16 v[110:113], v[222:225], v[202:205], v[110:113]
	v_mfma_f32_16x16x32_bf16 v[114:117], v[210:213], v[206:209], v[114:117]
	v_mfma_f32_16x16x32_bf16 v[118:121], v[214:217], v[206:209], v[118:121]
	v_mfma_f32_16x16x32_bf16 v[122:125], v[218:221], v[206:209], v[122:125]
	v_mfma_f32_16x16x32_bf16 v[126:129], v[222:225], v[206:209], v[126:129]
	s_setprio 0
	s_add_i32 s60, s60, 0x6000
	s_cmp_eq_u32 s60, 0x12000
	s_cselect_b32 s60, 0, s60
	s_add_u32 s54, s54, s72
	s_addc_u32 s55, s55, 0
	s_add_u32 s56, s56, s73
	s_addc_u32 s57, s57, 0
	s_add_i32 s61, s61, 0x6000
	s_cmp_eq_u32 s61, 0x12000
	s_cselect_b32 s61, 0, s61
	s_waitcnt vmcnt(6) lgkmcnt(0)
	s_barrier
	v_add_u32_e32 v240, s61, v238
	v_add_u32_e32 v241, s61, v239
	s_add_i32 m0, s60, s62
	v_mfma_f32_16x16x32_bf16 v[2:5], v[162:165], v[130:133], v[2:5]
	global_load_lds_dwordx4 v226, s[54:55]
	v_mfma_f32_16x16x32_bf16 v[6:9], v[166:169], v[130:133], v[6:9]
	global_load_lds_dwordx4 v226, s[54:55] offset:1024
	v_mfma_f32_16x16x32_bf16 v[10:13], v[170:173], v[130:133], v[10:13]
	global_load_lds_dwordx4 v226, s[54:55] offset:2048
	v_mfma_f32_16x16x32_bf16 v[14:17], v[174:177], v[130:133], v[14:17]
	global_load_lds_dwordx4 v226, s[54:55] offset:3072
	s_add_i32 m0, s60, s63
	v_mfma_f32_16x16x32_bf16 v[18:21], v[162:165], v[134:137], v[18:21]
	global_load_lds_dwordx4 v230, s[56:57]
	v_mfma_f32_16x16x32_bf16 v[22:25], v[166:169], v[134:137], v[22:25]
	global_load_lds_dwordx4 v231, s[56:57] offset:1024
	v_mfma_f32_16x16x32_bf16 v[26:29], v[170:173], v[134:137], v[26:29]
	v_mfma_f32_16x16x32_bf16 v[30:33], v[174:177], v[134:137], v[30:33]
	v_mfma_f32_16x16x32_bf16 v[34:37], v[162:165], v[138:141], v[34:37]
	ds_read_b128 v[210:213], v241 offset:0
	v_mfma_f32_16x16x32_bf16 v[38:41], v[166:169], v[138:141], v[38:41]
	ds_read_b128 v[214:217], v241 offset:256
	v_mfma_f32_16x16x32_bf16 v[42:45], v[170:173], v[138:141], v[42:45]
	ds_read_b128 v[218:221], v241 offset:512
	v_mfma_f32_16x16x32_bf16 v[46:49], v[174:177], v[138:141], v[46:49]
	ds_read_b128 v[222:225], v241 offset:768
	v_mfma_f32_16x16x32_bf16 v[50:53], v[162:165], v[142:145], v[50:53]
	ds_read_b128 v[178:181], v240 offset:0
	v_mfma_f32_16x16x32_bf16 v[54:57], v[166:169], v[142:145], v[54:57]
	ds_read_b128 v[182:185], v240 offset:1024
	v_mfma_f32_16x16x32_bf16 v[58:61], v[170:173], v[142:145], v[58:61]
	ds_read_b128 v[186:189], v240 offset:2048
	v_mfma_f32_16x16x32_bf16 v[62:65], v[174:177], v[142:145], v[62:65]
	ds_read_b128 v[190:193], v240 offset:3072
	v_mfma_f32_16x16x32_bf16 v[66:69], v[162:165], v[146:149], v[66:69]
	ds_read_b128 v[194:197], v240 offset:4096
	v_mfma_f32_16x16x32_bf16 v[70:73], v[166:169], v[146:149], v[70:73]
	ds_read_b128 v[198:201], v240 offset:5120
	v_mfma_f32_16x16x32_bf16 v[74:77], v[170:173], v[146:149], v[74:77]
	ds_read_b128 v[202:205], v240 offset:6144
	v_mfma_f32_16x16x32_bf16 v[78:81], v[174:177], v[146:149], v[78:81]
	ds_read_b128 v[206:209], v240 offset:7168
	s_setprio 1
	v_mfma_f32_16x16x32_bf16 v[82:85], v[162:165], v[150:153], v[82:85]
	v_mfma_f32_16x16x32_bf16 v[86:89], v[166:169], v[150:153], v[86:89]
	v_mfma_f32_16x16x32_bf16 v[90:93], v[170:173], v[150:153], v[90:93]
	v_mfma_f32_16x16x32_bf16 v[94:97], v[174:177], v[150:153], v[94:97]
	v_mfma_f32_16x16x32_bf16 v[98:101], v[162:165], v[154:157], v[98:101]
	v_mfma_f32_16x16x32_bf16 v[102:105], v[166:169], v[154:157], v[102:105]
	v_mfma_f32_16x16x32_bf16 v[106:109], v[170:173], v[154:157], v[106:109]
	v_mfma_f32_16x16x32_bf16 v[110:113], v[174:177], v[154:157], v[110:113]
	v_mfma_f32_16x16x32_bf16 v[114:117], v[162:165], v[158:161], v[114:117]
	v_mfma_f32_16x16x32_bf16 v[118:121], v[166:169], v[158:161], v[118:121]
	v_mfma_f32_16x16x32_bf16 v[122:125], v[170:173], v[158:161], v[122:125]
	v_mfma_f32_16x16x32_bf16 v[126:129], v[174:177], v[158:161], v[126:129]
	s_setprio 0
	s_add_i32 s60, s60, 0x6000
	s_cmp_eq_u32 s60, 0x12000
	s_cselect_b32 s60, 0, s60
	s_add_u32 s54, s54, s72
	s_addc_u32 s55, s55, 0
	s_add_u32 s56, s56, s73
	s_addc_u32 s57, s57, 0
	s_add_i32 s61, s61, 0x6000
	s_cmp_eq_u32 s61, 0x12000
	s_cselect_b32 s61, 0, s61
	s_waitcnt vmcnt(6) lgkmcnt(0)
	s_barrier
	v_add_u32_e32 v240, s61, v238
	v_add_u32_e32 v241, s61, v239
	s_add_i32 m0, s60, s62
	v_mfma_f32_16x16x32_bf16 v[2:5], v[210:213], v[178:181], v[2:5]
	global_load_lds_dwordx4 v226, s[54:55]
	v_mfma_f32_16x16x32_bf16 v[6:9], v[214:217], v[178:181], v[6:9]
	global_load_lds_dwordx4 v226, s[54:55] offset:1024
	v_mfma_f32_16x16x32_bf16 v[10:13], v[218:221], v[178:181], v[10:13]
	global_load_lds_dwordx4 v226, s[54:55] offset:2048
	v_mfma_f32_16x16x32_bf16 v[14:17], v[222:225], v[178:181], v[14:17]
	global_load_lds_dwordx4 v226, s[54:55] offset:3072
	s_add_i32 m0, s60, s63
	v_mfma_f32_16x16x32_bf16 v[18:21], v[210:213], v[182:185], v[18:21]
	global_load_lds_dwordx4 v230, s[56:57]
	v_mfma_f32_16x16x32_bf16 v[22:25], v[214:217], v[182:185], v[22:25]
	global_load_lds_dwordx4 v231, s[56:57] offset:1024
	v_mfma_f32_16x16x32_bf16 v[26:29], v[218:221], v[182:185], v[26:29]
	v_mfma_f32_16x16x32_bf16 v[30:33], v[222:225], v[182:185], v[30:33]
	v_mfma_f32_16x16x32_bf16 v[34:37], v[210:213], v[186:189], v[34:37]
	ds_read_b128 v[162:165], v241 offset:0
	v_mfma_f32_16x16x32_bf16 v[38:41], v[214:217], v[186:189], v[38:41]
	ds_read_b128 v[166:169], v241 offset:256
	v_mfma_f32_16x16x32_bf16 v[42:45], v[218:221], v[186:189], v[42:45]
	ds_read_b128 v[170:173], v241 offset:512
	v_mfma_f32_16x16x32_bf16 v[46:49], v[222:225], v[186:189], v[46:49]
	ds_read_b128 v[174:177], v241 offset:768
	v_mfma_f32_16x16x32_bf16 v[50:53], v[210:213], v[190:193], v[50:53]
	ds_read_b128 v[130:133], v240 offset:0
	v_mfma_f32_16x16x32_bf16 v[54:57], v[214:217], v[190:193], v[54:57]
	ds_read_b128 v[134:137], v240 offset:1024
	v_mfma_f32_16x16x32_bf16 v[58:61], v[218:221], v[190:193], v[58:61]
	ds_read_b128 v[138:141], v240 offset:2048
	v_mfma_f32_16x16x32_bf16 v[62:65], v[222:225], v[190:193], v[62:65]
	ds_read_b128 v[142:145], v240 offset:3072
	v_mfma_f32_16x16x32_bf16 v[66:69], v[210:213], v[194:197], v[66:69]
	ds_read_b128 v[146:149], v240 offset:4096
	v_mfma_f32_16x16x32_bf16 v[70:73], v[214:217], v[194:197], v[70:73]
	ds_read_b128 v[150:153], v240 offset:5120
	v_mfma_f32_16x16x32_bf16 v[74:77], v[218:221], v[194:197], v[74:77]
	ds_read_b128 v[154:157], v240 offset:6144
	v_mfma_f32_16x16x32_bf16 v[78:81], v[222:225], v[194:197], v[78:81]
	ds_read_b128 v[158:161], v240 offset:7168
	s_setprio 1
	v_mfma_f32_16x16x32_bf16 v[82:85], v[210:213], v[198:201], v[82:85]
	v_mfma_f32_16x16x32_bf16 v[86:89], v[214:217], v[198:201], v[86:89]
	v_mfma_f32_16x16x32_bf16 v[90:93], v[218:221], v[198:201], v[90:93]
	v_mfma_f32_16x16x32_bf16 v[94:97], v[222:225], v[198:201], v[94:97]
	v_mfma_f32_16x16x32_bf16 v[98:101], v[210:213], v[202:205], v[98:101]
	v_mfma_f32_16x16x32_bf16 v[102:105], v[214:217], v[202:205], v[102:105]
	v_mfma_f32_16x16x32_bf16 v[106:109], v[218:221], v[202:205], v[106:109]
	v_mfma_f32_16x16x32_bf16 v[110:113], v[222:225], v[202:205], v[110:113]
	v_mfma_f32_16x16x32_bf16 v[114:117], v[210:213], v[206:209], v[114:117]
	v_mfma_f32_16x16x32_bf16 v[118:121], v[214:217], v[206:209], v[118:121]
	v_mfma_f32_16x16x32_bf16 v[122:125], v[218:221], v[206:209], v[122:125]
	v_mfma_f32_16x16x32_bf16 v[126:129], v[222:225], v[206:209], v[126:129]
	s_setprio 0
	s_add_i32 s60, s60, 0x6000
	s_cmp_eq_u32 s60, 0x12000
	s_cselect_b32 s60, 0, s60
	s_add_u32 s54, s54, s72
	s_addc_u32 s55, s55, 0
	s_add_u32 s56, s56, s73
	s_addc_u32 s57, s57, 0
	s_add_i32 s61, s61, 0x6000
	s_cmp_eq_u32 s61, 0x12000
	s_cselect_b32 s61, 0, s61
	s_nop 7
	s_nop 1
	s_lshl_b32 s26, s35, 11
	s_lshl_b32 s27, s36, 1
	s_add_i32 s26, s26, s27
	s_add_u32 s18, s52, s26
	s_addc_u32 s19, s53, 0
	v_cvt_pk_bf16_f32 v2, v2, v3
	v_cvt_pk_bf16_f32 v3, v4, v5
	v_cvt_pk_bf16_f32 v4, v6, v7
	v_cvt_pk_bf16_f32 v5, v8, v9
	v_cvt_pk_bf16_f32 v6, v10, v11
	v_cvt_pk_bf16_f32 v7, v12, v13
	v_cvt_pk_bf16_f32 v8, v14, v15
	v_cvt_pk_bf16_f32 v9, v16, v17
	global_store_dwordx4 v242, v[2:5], s[18:19]
	global_store_dwordx4 v242, v[6:9], s[18:19] offset:16
	s_add_u32 s18, s18, 0x8000
	s_addc_u32 s19, s19, 0
	v_cvt_pk_bf16_f32 v18, v18, v19
	v_cvt_pk_bf16_f32 v19, v20, v21
	v_cvt_pk_bf16_f32 v20, v22, v23
	v_cvt_pk_bf16_f32 v21, v24, v25
	v_cvt_pk_bf16_f32 v22, v26, v27
	v_cvt_pk_bf16_f32 v23, v28, v29
	v_cvt_pk_bf16_f32 v24, v30, v31
	v_cvt_pk_bf16_f32 v25, v32, v33
	global_store_dwordx4 v242, v[18:21], s[18:19]
	global_store_dwordx4 v242, v[22:25], s[18:19] offset:16
	s_add_u32 s18, s18, 0x8000
	s_addc_u32 s19, s19, 0
	v_cvt_pk_bf16_f32 v34, v34, v35
	v_cvt_pk_bf16_f32 v35, v36, v37
	v_cvt_pk_bf16_f32 v36, v38, v39
	v_cvt_pk_bf16_f32 v37, v40, v41
	v_cvt_pk_bf16_f32 v38, v42, v43
	v_cvt_pk_bf16_f32 v39, v44, v45
	v_cvt_pk_bf16_f32 v40, v46, v47
	v_cvt_pk_bf16_f32 v41, v48, v49
	global_store_dwordx4 v242, v[34:37], s[18:19]
	global_store_dwordx4 v242, v[38:41], s[18:19] offset:16
	s_add_u32 s18, s18, 0x8000
	s_addc_u32 s19, s19, 0
	v_cvt_pk_bf16_f32 v50, v50, v51
	v_cvt_pk_bf16_f32 v51, v52, v53
	v_cvt_pk_bf16_f32 v52, v54, v55
	v_cvt_pk_bf16_f32 v53, v56, v57
	v_cvt_pk_bf16_f32 v54, v58, v59
	v_cvt_pk_bf16_f32 v55, v60, v61
	v_cvt_pk_bf16_f32 v56, v62, v63
	v_cvt_pk_bf16_f32 v57, v64, v65
	global_store_dwordx4 v242, v[50:53], s[18:19]
	global_store_dwordx4 v242, v[54:57], s[18:19] offset:16
	s_add_u32 s18, s18, 0x8000
	s_addc_u32 s19, s19, 0
	v_cvt_pk_bf16_f32 v66, v66, v67
	v_cvt_pk_bf16_f32 v67, v68, v69
	v_cvt_pk_bf16_f32 v68, v70, v71
	v_cvt_pk_bf16_f32 v69, v72, v73
	v_cvt_pk_bf16_f32 v70, v74, v75
	v_cvt_pk_bf16_f32 v71, v76, v77
	v_cvt_pk_bf16_f32 v72, v78, v79
	v_cvt_pk_bf16_f32 v73, v80, v81
	global_store_dwordx4 v242, v[66:69], s[18:19]
	global_store_dwordx4 v242, v[70:73], s[18:19] offset:16
	s_add_u32 s18, s18, 0x8000
	s_addc_u32 s19, s19, 0
	v_cvt_pk_bf16_f32 v82, v82, v83
	v_cvt_pk_bf16_f32 v83, v84, v85
	v_cvt_pk_bf16_f32 v84, v86, v87
	v_cvt_pk_bf16_f32 v85, v88, v89
	v_cvt_pk_bf16_f32 v86, v90, v91
	v_cvt_pk_bf16_f32 v87, v92, v93
	v_cvt_pk_bf16_f32 v88, v94, v95
	v_cvt_pk_bf16_f32 v89, v96, v97
	global_store_dwordx4 v242, v[82:85], s[18:19]
	global_store_dwordx4 v242, v[86:89], s[18:19] offset:16
	s_add_u32 s18, s18, 0x8000
	s_addc_u32 s19, s19, 0
	v_cvt_pk_bf16_f32 v98, v98, v99
	v_cvt_pk_bf16_f32 v99, v100, v101
	v_cvt_pk_bf16_f32 v100, v102, v103
	v_cvt_pk_bf16_f32 v101, v104, v105
	v_cvt_pk_bf16_f32 v102, v106, v107
	v_cvt_pk_bf16_f32 v103, v108, v109
	v_cvt_pk_bf16_f32 v104, v110, v111
	v_cvt_pk_bf16_f32 v105, v112, v113
	global_store_dwordx4 v242, v[98:101], s[18:19]
	global_store_dwordx4 v242, v[102:105], s[18:19] offset:16
	s_add_u32 s18, s18, 0x8000
	s_addc_u32 s19, s19, 0
	v_cvt_pk_bf16_f32 v114, v114, v115
	v_cvt_pk_bf16_f32 v115, v116, v117
	v_cvt_pk_bf16_f32 v116, v118, v119
	v_cvt_pk_bf16_f32 v117, v120, v121
	v_cvt_pk_bf16_f32 v118, v122, v123
	v_cvt_pk_bf16_f32 v119, v124, v125
	v_cvt_pk_bf16_f32 v120, v126, v127
	v_cvt_pk_bf16_f32 v121, v128, v129
	global_store_dwordx4 v242, v[114:117], s[18:19]
	global_store_dwordx4 v242, v[118:121], s[18:19] offset:16
	s_mov_b32 s34, s38
	s_mov_b32 s35, s30
	s_mov_b32 s36, s31
	s_branch .Lgy_tile

.Lup_kdone:
	s_cmp_eq_u32 s37, 0
	s_cbranch_scc1 .Lup_tail_last
	s_waitcnt vmcnt(6) lgkmcnt(0)
	s_barrier
	v_add_u32_e32 v240, s61, v238
	v_add_u32_e32 v241, s61, v239
	s_add_i32 m0, s60, s62
	v_mfma_f32_16x16x32_bf16 v[2:5], v[162:165], v[130:133], v[2:5]
	global_load_lds_dwordx4 v226, s[54:55]
	v_mfma_f32_16x16x32_bf16 v[6:9], v[166:169], v[130:133], v[6:9]
	global_load_lds_dwordx4 v226, s[54:55] offset:1024
	v_mfma_f32_16x16x32_bf16 v[10:13], v[170:173], v[130:133], v[10:13]
	global_load_lds_dwordx4 v226, s[54:55] offset:2048
	v_mfma_f32_16x16x32_bf16 v[14:17], v[174:177], v[130:133], v[14:17]
	global_load_lds_dwordx4 v226, s[54:55] offset:3072
	s_add_i32 m0, s60, s63
	v_mfma_f32_16x16x32_bf16 v[18:21], v[162:165], v[134:137], v[18:21]
	global_load_lds_dwordx4 v230, s[56:57]
	v_mfma_f32_16x16x32_bf16 v[22:25], v[166:169], v[134:137], v[22:25]
	global_load_lds_dwordx4 v231, s[56:57] offset:1024
	v_mfma_f32_16x16x32_bf16 v[26:29], v[170:173], v[134:137], v[26:29]
	v_mfma_f32_16x16x32_bf16 v[30:33], v[174:177], v[134:137], v[30:33]
	v_mfma_f32_16x16x32_bf16 v[34:37], v[162:165], v[138:141], v[34:37]
	ds_read_b128 v[210:213], v241 offset:0
	v_mfma_f32_16x16x32_bf16 v[38:41], v[166:169], v[138:141], v[38:41]
	ds_read_b128 v[214:217], v241 offset:256
	v_mfma_f32_16x16x32_bf16 v[42:45], v[170:173], v[138:141], v[42:45]
	ds_read_b128 v[218:221], v241 offset:2048
	v_mfma_f32_16x16x32_bf16 v[46:49], v[174:177], v[138:141], v[46:49]
	ds_read_b128 v[222:225], v241 offset:2304
	v_mfma_f32_16x16x32_bf16 v[50:53], v[162:165], v[142:145], v[50:53]
	ds_read_b128 v[178:181], v240 offset:0
	v_mfma_f32_16x16x32_bf16 v[54:57], v[166:169], v[142:145], v[54:57]
	ds_read_b128 v[182:185], v240 offset:1024
	v_mfma_f32_16x16x32_bf16 v[58:61], v[170:173], v[142:145], v[58:61]
	ds_read_b128 v[186:189], v240 offset:2048
	v_mfma_f32_16x16x32_bf16 v[62:65], v[174:177], v[142:145], v[62:65]
	ds_read_b128 v[190:193], v240 offset:3072
	v_mfma_f32_16x16x32_bf16 v[66:69], v[162:165], v[146:149], v[66:69]
	ds_read_b128 v[194:197], v240 offset:4096
	v_mfma_f32_16x16x32_bf16 v[70:73], v[166:169], v[146:149], v[70:73]
	ds_read_b128 v[198:201], v240 offset:5120
	v_mfma_f32_16x16x32_bf16 v[74:77], v[170:173], v[146:149], v[74:77]
	ds_read_b128 v[202:205], v240 offset:6144
	v_mfma_f32_16x16x32_bf16 v[78:81], v[174:177], v[146:149], v[78:81]
	ds_read_b128 v[206:209], v240 offset:7168
	s_setprio 1
	v_mfma_f32_16x16x32_bf16 v[82:85], v[162:165], v[150:153], v[82:85]
	v_mfma_f32_16x16x32_bf16 v[86:89], v[166:169], v[150:153], v[86:89]
	v_mfma_f32_16x16x32_bf16 v[90:93], v[170:173], v[150:153], v[90:93]
	v_mfma_f32_16x16x32_bf16 v[94:97], v[174:177], v[150:153], v[94:97]
	v_mfma_f32_16x16x32_bf16 v[98:101], v[162:165], v[154:157], v[98:101]
	v_mfma_f32_16x16x32_bf16 v[102:105], v[166:169], v[154:157], v[102:105]
	v_mfma_f32_16x16x32_bf16 v[106:109], v[170:173], v[154:157], v[106:109]
	v_mfma_f32_16x16x32_bf16 v[110:113], v[174:177], v[154:157], v[110:113]
	v_mfma_f32_16x16x32_bf16 v[114:117], v[162:165], v[158:161], v[114:117]
	v_mfma_f32_16x16x32_bf16 v[118:121], v[166:169], v[158:161], v[118:121]
	v_mfma_f32_16x16x32_bf16 v[122:125], v[170:173], v[158:161], v[122:125]
	v_mfma_f32_16x16x32_bf16 v[126:129], v[174:177], v[158:161], v[126:129]
	s_setprio 0
	s_add_i32 s60, s60, 0x6000
	s_cmp_eq_u32 s60, 0x12000
	s_cselect_b32 s60, 0, s60
	s_add_u32 s54, s54, s72
	s_addc_u32 s55, s55, 0
	s_add_u32 s56, s56, s73
	s_addc_u32 s57, s57, 0
	s_add_i32 s61, s61, 0x6000
	s_cmp_eq_u32 s61, 0x12000
	s_cselect_b32 s61, 0, s61
	v_mov_b32_e32 v226, v232
	v_mov_b32_e32 v230, v236
	v_mov_b32_e32 v231, v237
	s_mov_b64 s[54:55], s[48:49]
	s_mov_b64 s[56:57], s[50:51]
	s_waitcnt vmcnt(6) lgkmcnt(0)
	s_barrier
	v_add_u32_e32 v240, s61, v238
	v_add_u32_e32 v241, s61, v239
	s_add_i32 m0, s60, s62
	v_mfma_f32_16x16x32_bf16 v[2:5], v[210:213], v[178:181], v[2:5]
	global_load_lds_dwordx4 v226, s[54:55]
	v_mfma_f32_16x16x32_bf16 v[6:9], v[214:217], v[178:181], v[6:9]
	global_load_lds_dwordx4 v226, s[54:55] offset:1024
	v_mfma_f32_16x16x32_bf16 v[10:13], v[218:221], v[178:181], v[10:13]
	global_load_lds_dwordx4 v226, s[54:55] offset:2048
	v_mfma_f32_16x16x32_bf16 v[14:17], v[222:225], v[178:181], v[14:17]
	global_load_lds_dwordx4 v226, s[54:55] offset:3072
	s_add_i32 m0, s60, s63
	v_mfma_f32_16x16x32_bf16 v[18:21], v[210:213], v[182:185], v[18:21]
	global_load_lds_dwordx4 v230, s[56:57]
	v_mfma_f32_16x16x32_bf16 v[22:25], v[214:217], v[182:185], v[22:25]
	global_load_lds_dwordx4 v231, s[56:57] offset:1024
	v_mfma_f32_16x16x32_bf16 v[26:29], v[218:221], v[182:185], v[26:29]
	v_mfma_f32_16x16x32_bf16 v[30:33], v[222:225], v[182:185], v[30:33]
	v_mfma_f32_16x16x32_bf16 v[34:37], v[210:213], v[186:189], v[34:37]
	ds_read_b128 v[162:165], v241 offset:0
	v_mfma_f32_16x16x32_bf16 v[38:41], v[214:217], v[186:189], v[38:41]
	ds_read_b128 v[166:169], v241 offset:256
	v_mfma_f32_16x16x32_bf16 v[42:45], v[218:221], v[186:189], v[42:45]
	ds_read_b128 v[170:173], v241 offset:2048
	v_mfma_f32_16x16x32_bf16 v[46:49], v[222:225], v[186:189], v[46:49]
	ds_read_b128 v[174:177], v241 offset:2304
	v_mfma_f32_16x16x32_bf16 v[50:53], v[210:213], v[190:193], v[50:53]
	ds_read_b128 v[130:133], v240 offset:0
	v_mfma_f32_16x16x32_bf16 v[54:57], v[214:217], v[190:193], v[54:57]
	ds_read_b128 v[134:137], v240 offset:1024
	v_mfma_f32_16x16x32_bf16 v[58:61], v[218:221], v[190:193], v[58:61]
	ds_read_b128 v[138:141], v240 offset:2048
	v_mfma_f32_16x16x32_bf16 v[62:65], v[222:225], v[190:193], v[62:65]
	ds_read_b128 v[142:145], v240 offset:3072
	v_mfma_f32_16x16x32_bf16 v[66:69], v[210:213], v[194:197], v[66:69]
	ds_read_b128 v[146:149], v240 offset:4096
	v_mfma_f32_16x16x32_bf16 v[70:73], v[214:217], v[194:197], v[70:73]
	ds_read_b128 v[150:153], v240 offset:5120
	v_mfma_f32_16x16x32_bf16 v[74:77], v[218:221], v[194:197], v[74:77]
	ds_read_b128 v[154:157], v240 offset:6144
	v_mfma_f32_16x16x32_bf16 v[78:81], v[222:225], v[194:197], v[78:81]
	ds_read_b128 v[158:161], v240 offset:7168
	s_setprio 1
	v_mfma_f32_16x16x32_bf16 v[82:85], v[210:213], v[198:201], v[82:85]
	v_mfma_f32_16x16x32_bf16 v[86:89], v[214:217], v[198:201], v[86:89]
	v_mfma_f32_16x16x32_bf16 v[90:93], v[218:221], v[198:201], v[90:93]
	v_mfma_f32_16x16x32_bf16 v[94:97], v[222:225], v[198:201], v[94:97]
	v_mfma_f32_16x16x32_bf16 v[98:101], v[210:213], v[202:205], v[98:101]
	v_mfma_f32_16x16x32_bf16 v[102:105], v[214:217], v[202:205], v[102:105]
	v_mfma_f32_16x16x32_bf16 v[106:109], v[218:221], v[202:205], v[106:109]
	v_mfma_f32_16x16x32_bf16 v[110:113], v[222:225], v[202:205], v[110:113]
	v_mfma_f32_16x16x32_bf16 v[114:117], v[210:213], v[206:209], v[114:117]
	v_mfma_f32_16x16x32_bf16 v[118:121], v[214:217], v[206:209], v[118:121]
	v_mfma_f32_16x16x32_bf16 v[122:125], v[218:221], v[206:209], v[122:125]
	v_mfma_f32_16x16x32_bf16 v[126:129], v[222:225], v[206:209], v[126:129]
	s_setprio 0
	s_add_i32 s60, s60, 0x6000
	s_cmp_eq_u32 s60, 0x12000
	s_cselect_b32 s60, 0, s60
	s_add_u32 s54, s54, s72
	s_addc_u32 s55, s55, 0
	s_add_u32 s56, s56, s73
	s_addc_u32 s57, s57, 0
	s_add_i32 s61, s61, 0x6000
	s_cmp_eq_u32 s61, 0x12000
	s_cselect_b32 s61, 0, s61
	s_waitcnt vmcnt(6) lgkmcnt(0)
	s_barrier
	v_add_u32_e32 v240, s61, v238
	v_add_u32_e32 v241, s61, v239
	s_add_i32 m0, s60, s62
	v_mfma_f32_16x16x32_bf16 v[2:5], v[162:165], v[130:133], v[2:5]
	global_load_lds_dwordx4 v226, s[54:55]
	v_mfma_f32_16x16x32_bf16 v[6:9], v[166:169], v[130:133], v[6:9]
	global_load_lds_dwordx4 v226, s[54:55] offset:1024
	v_mfma_f32_16x16x32_bf16 v[10:13], v[170:173], v[130:133], v[10:13]
	global_load_lds_dwordx4 v226, s[54:55] offset:2048
	v_mfma_f32_16x16x32_bf16 v[14:17], v[174:177], v[130:133], v[14:17]
	global_load_lds_dwordx4 v226, s[54:55] offset:3072
	s_add_i32 m0, s60, s63
	v_mfma_f32_16x16x32_bf16 v[18:21], v[162:165], v[134:137], v[18:21]
	global_load_lds_dwordx4 v230, s[56:57]
	v_mfma_f32_16x16x32_bf16 v[22:25], v[166:169], v[134:137], v[22:25]
	global_load_lds_dwordx4 v231, s[56:57] offset:1024
	v_mfma_f32_16x16x32_bf16 v[26:29], v[170:173], v[134:137], v[26:29]
	v_mfma_f32_16x16x32_bf16 v[30:33], v[174:177], v[134:137], v[30:33]
	v_mfma_f32_16x16x32_bf16 v[34:37], v[162:165], v[138:141], v[34:37]
	ds_read_b128 v[210:213], v241 offset:0
	v_mfma_f32_16x16x32_bf16 v[38:41], v[166:169], v[138:141], v[38:41]
	ds_read_b128 v[214:217], v241 offset:256
	v_mfma_f32_16x16x32_bf16 v[42:45], v[170:173], v[138:141], v[42:45]
	ds_read_b128 v[218:221], v241 offset:2048
	v_mfma_f32_16x16x32_bf16 v[46:49], v[174:177], v[138:141], v[46:49]
	ds_read_b128 v[222:225], v241 offset:2304
	v_mfma_f32_16x16x32_bf16 v[50:53], v[162:165], v[142:145], v[50:53]
	ds_read_b128 v[178:181], v240 offset:0
	v_mfma_f32_16x16x32_bf16 v[54:57], v[166:169], v[142:145], v[54:57]
	ds_read_b128 v[182:185], v240 offset:1024
	v_mfma_f32_16x16x32_bf16 v[58:61], v[170:173], v[142:145], v[58:61]
	ds_read_b128 v[186:189], v240 offset:2048
	v_mfma_f32_16x16x32_bf16 v[62:65], v[174:177], v[142:145], v[62:65]
	ds_read_b128 v[190:193], v240 offset:3072
	v_mfma_f32_16x16x32_bf16 v[66:69], v[162:165], v[146:149], v[66:69]
	ds_read_b128 v[194:197], v240 offset:4096
	v_mfma_f32_16x16x32_bf16 v[70:73], v[166:169], v[146:149], v[70:73]
	ds_read_b128 v[198:201], v240 offset:5120
	v_mfma_f32_16x16x32_bf16 v[74:77], v[170:173], v[146:149], v[74:77]
	ds_read_b128 v[202:205], v240 offset:6144
	v_mfma_f32_16x16x32_bf16 v[78:81], v[174:177], v[146:149], v[78:81]
	ds_read_b128 v[206:209], v240 offset:7168
	s_setprio 1
	v_mfma_f32_16x16x32_bf16 v[82:85], v[162:165], v[150:153], v[82:85]
	v_mfma_f32_16x16x32_bf16 v[86:89], v[166:169], v[150:153], v[86:89]
	v_mfma_f32_16x16x32_bf16 v[90:93], v[170:173], v[150:153], v[90:93]
	v_mfma_f32_16x16x32_bf16 v[94:97], v[174:177], v[150:153], v[94:97]
	v_mfma_f32_16x16x32_bf16 v[98:101], v[162:165], v[154:157], v[98:101]
	v_mfma_f32_16x16x32_bf16 v[102:105], v[166:169], v[154:157], v[102:105]
	v_mfma_f32_16x16x32_bf16 v[106:109], v[170:173], v[154:157], v[106:109]
	v_mfma_f32_16x16x32_bf16 v[110:113], v[174:177], v[154:157], v[110:113]
	v_mfma_f32_16x16x32_bf16 v[114:117], v[162:165], v[158:161], v[114:117]
	v_mfma_f32_16x16x32_bf16 v[118:121], v[166:169], v[158:161], v[118:121]
	v_mfma_f32_16x16x32_bf16 v[122:125], v[170:173], v[158:161], v[122:125]
	v_mfma_f32_16x16x32_bf16 v[126:129], v[174:177], v[158:161], v[126:129]
	s_setprio 0
	s_add_i32 s60, s60, 0x6000
	s_cmp_eq_u32 s60, 0x12000
	s_cselect_b32 s60, 0, s60
	s_add_u32 s54, s54, s72
	s_addc_u32 s55, s55, 0
	s_add_u32 s56, s56, s73
	s_addc_u32 s57, s57, 0
	s_add_i32 s61, s61, 0x6000
	s_cmp_eq_u32 s61, 0x12000
	s_cselect_b32 s61, 0, s61
	s_waitcnt vmcnt(6) lgkmcnt(0)
	s_barrier
	v_add_u32_e32 v240, s61, v238
	v_add_u32_e32 v241, s61, v239
	s_add_i32 m0, s60, s62
	v_mfma_f32_16x16x32_bf16 v[2:5], v[210:213], v[178:181], v[2:5]
	global_load_lds_dwordx4 v226, s[54:55]
	v_mfma_f32_16x16x32_bf16 v[6:9], v[214:217], v[178:181], v[6:9]
	global_load_lds_dwordx4 v226, s[54:55] offset:1024
	v_mfma_f32_16x16x32_bf16 v[10:13], v[218:221], v[178:181], v[10:13]
	global_load_lds_dwordx4 v226, s[54:55] offset:2048
	v_mfma_f32_16x16x32_bf16 v[14:17], v[222:225], v[178:181], v[14:17]
	global_load_lds_dwordx4 v226, s[54:55] offset:3072
	s_add_i32 m0, s60, s63
	v_mfma_f32_16x16x32_bf16 v[18:21], v[210:213], v[182:185], v[18:21]
	global_load_lds_dwordx4 v230, s[56:57]
	v_mfma_f32_16x16x32_bf16 v[22:25], v[214:217], v[182:185], v[22:25]
	global_load_lds_dwordx4 v231, s[56:57] offset:1024
	v_mfma_f32_16x16x32_bf16 v[26:29], v[218:221], v[182:185], v[26:29]
	v_mfma_f32_16x16x32_bf16 v[30:33], v[222:225], v[182:185], v[30:33]
	v_mfma_f32_16x16x32_bf16 v[34:37], v[210:213], v[186:189], v[34:37]
	ds_read_b128 v[162:165], v241 offset:0
	v_mfma_f32_16x16x32_bf16 v[38:41], v[214:217], v[186:189], v[38:41]
	ds_read_b128 v[166:169], v241 offset:256
	v_mfma_f32_16x16x32_bf16 v[42:45], v[218:221], v[186:189], v[42:45]
	ds_read_b128 v[170:173], v241 offset:2048
	v_mfma_f32_16x16x32_bf16 v[46:49], v[222:225], v[186:189], v[46:49]
	ds_read_b128 v[174:177], v241 offset:2304
	v_mfma_f32_16x16x32_bf16 v[50:53], v[210:213], v[190:193], v[50:53]
	ds_read_b128 v[130:133], v240 offset:0
	v_mfma_f32_16x16x32_bf16 v[54:57], v[214:217], v[190:193], v[54:57]
	ds_read_b128 v[134:137], v240 offset:1024
	v_mfma_f32_16x16x32_bf16 v[58:61], v[218:221], v[190:193], v[58:61]
	ds_read_b128 v[138:141], v240 offset:2048
	v_mfma_f32_16x16x32_bf16 v[62:65], v[222:225], v[190:193], v[62:65]
	ds_read_b128 v[142:145], v240 offset:3072
	v_mfma_f32_16x16x32_bf16 v[66:69], v[210:213], v[194:197], v[66:69]
	ds_read_b128 v[146:149], v240 offset:4096
	v_mfma_f32_16x16x32_bf16 v[70:73], v[214:217], v[194:197], v[70:73]
	ds_read_b128 v[150:153], v240 offset:5120
	v_mfma_f32_16x16x32_bf16 v[74:77], v[218:221], v[194:197], v[74:77]
	ds_read_b128 v[154:157], v240 offset:6144
	v_mfma_f32_16x16x32_bf16 v[78:81], v[222:225], v[194:197], v[78:81]
	ds_read_b128 v[158:161], v240 offset:7168
	s_setprio 1
	v_mfma_f32_16x16x32_bf16 v[82:85], v[210:213], v[198:201], v[82:85]
	v_mfma_f32_16x16x32_bf16 v[86:89], v[214:217], v[198:201], v[86:89]
	v_mfma_f32_16x16x32_bf16 v[90:93], v[218:221], v[198:201], v[90:93]
	v_mfma_f32_16x16x32_bf16 v[94:97], v[222:225], v[198:201], v[94:97]
	v_mfma_f32_16x16x32_bf16 v[98:101], v[210:213], v[202:205], v[98:101]
	v_mfma_f32_16x16x32_bf16 v[102:105], v[214:217], v[202:205], v[102:105]
	v_mfma_f32_16x16x32_bf16 v[106:109], v[218:221], v[202:205], v[106:109]
	v_mfma_f32_16x16x32_bf16 v[110:113], v[222:225], v[202:205], v[110:113]
	v_mfma_f32_16x16x32_bf16 v[114:117], v[210:213], v[206:209], v[114:117]
	v_mfma_f32_16x16x32_bf16 v[118:121], v[214:217], v[206:209], v[118:121]
	v_mfma_f32_16x16x32_bf16 v[122:125], v[218:221], v[206:209], v[122:125]
	v_mfma_f32_16x16x32_bf16 v[126:129], v[222:225], v[206:209], v[126:129]
	s_setprio 0
	s_add_i32 s60, s60, 0x6000
	s_cmp_eq_u32 s60, 0x12000
	s_cselect_b32 s60, 0, s60
	s_add_u32 s54, s54, s72
	s_addc_u32 s55, s55, 0
	s_add_u32 s56, s56, s73
	s_addc_u32 s57, s57, 0
	s_add_i32 s61, s61, 0x6000
	s_cmp_eq_u32 s61, 0x12000
	s_cselect_b32 s61, 0, s61
	s_and_b32 s39, s35, 0xfff
	s_lshr_b32 s21, s36, 7
	s_waitcnt vmcnt(18)
	v_mbcnt_lo_u32_b32 v217, -1, 0
	v_mbcnt_hi_u32_b32 v217, -1, v217
	v_lshlrev_b32_e32 v217, 5, v217
	s_lshl_b32 s26, s43, 11
	s_add_i32 s26, s26, 0x12010
	v_add_u32_e32 v217, s26, v217
	s_cmp_eq_u32 s42, 0
	s_cbranch_scc0 .Lup_en_nowr
	ds_write_b128 v217, v[114:117]
	ds_write_b128 v217, v[118:121] offset:16

.Lpj_kdone:
	s_cmp_eq_u32 s37, 0
	s_cbranch_scc1 .Lpj_tail_last
	s_waitcnt vmcnt(6) lgkmcnt(0)
	s_barrier
	v_add_u32_e32 v240, s61, v238
	v_add_u32_e32 v241, s61, v239
	s_add_i32 m0, s60, s62
	v_mfma_f32_16x16x32_bf16 v[2:5], v[162:165], v[130:133], v[2:5]
	global_load_lds_dwordx4 v226, s[54:55]
	v_mfma_f32_16x16x32_bf16 v[6:9], v[166:169], v[130:133], v[6:9]
	global_load_lds_dwordx4 v226, s[54:55] offset:1024
	v_mfma_f32_16x16x32_bf16 v[10:13], v[170:173], v[130:133], v[10:13]
	global_load_lds_dwordx4 v226, s[54:55] offset:2048
	v_mfma_f32_16x16x32_bf16 v[14:17], v[174:177], v[130:133], v[14:17]
	global_load_lds_dwordx4 v226, s[54:55] offset:3072
	s_add_i32 m0, s60, s63
	v_mfma_f32_16x16x32_bf16 v[18:21], v[162:165], v[134:137], v[18:21]
	global_load_lds_dwordx4 v230, s[56:57]
	v_mfma_f32_16x16x32_bf16 v[22:25], v[166:169], v[134:137], v[22:25]
	global_load_lds_dwordx4 v231, s[56:57] offset:1024
	v_mfma_f32_16x16x32_bf16 v[26:29], v[170:173], v[134:137], v[26:29]
	v_mfma_f32_16x16x32_bf16 v[30:33], v[174:177], v[134:137], v[30:33]
	v_mfma_f32_16x16x32_bf16 v[34:37], v[162:165], v[138:141], v[34:37]
	ds_read_b128 v[210:213], v241 offset:0
	v_mfma_f32_16x16x32_bf16 v[38:41], v[166:169], v[138:141], v[38:41]
	ds_read_b128 v[214:217], v241 offset:256
	v_mfma_f32_16x16x32_bf16 v[42:45], v[170:173], v[138:141], v[42:45]
	ds_read_b128 v[218:221], v241 offset:2048
	v_mfma_f32_16x16x32_bf16 v[46:49], v[174:177], v[138:141], v[46:49]
	ds_read_b128 v[222:225], v241 offset:2304
	v_mfma_f32_16x16x32_bf16 v[50:53], v[162:165], v[142:145], v[50:53]
	ds_read_b128 v[178:181], v240 offset:0
	v_mfma_f32_16x16x32_bf16 v[54:57], v[166:169], v[142:145], v[54:57]
	ds_read_b128 v[182:185], v240 offset:1024
	v_mfma_f32_16x16x32_bf16 v[58:61], v[170:173], v[142:145], v[58:61]
	ds_read_b128 v[186:189], v240 offset:2048
	v_mfma_f32_16x16x32_bf16 v[62:65], v[174:177], v[142:145], v[62:65]
	ds_read_b128 v[190:193], v240 offset:3072
	v_mfma_f32_16x16x32_bf16 v[66:69], v[162:165], v[146:149], v[66:69]
	ds_read_b128 v[194:197], v240 offset:4096
	v_mfma_f32_16x16x32_bf16 v[70:73], v[166:169], v[146:149], v[70:73]
	ds_read_b128 v[198:201], v240 offset:5120
	v_mfma_f32_16x16x32_bf16 v[74:77], v[170:173], v[146:149], v[74:77]
	ds_read_b128 v[202:205], v240 offset:6144
	v_mfma_f32_16x16x32_bf16 v[78:81], v[174:177], v[146:149], v[78:81]
	ds_read_b128 v[206:209], v240 offset:7168
	s_setprio 1
	v_mfma_f32_16x16x32_bf16 v[82:85], v[162:165], v[150:153], v[82:85]
	v_mfma_f32_16x16x32_bf16 v[86:89], v[166:169], v[150:153], v[86:89]
	v_mfma_f32_16x16x32_bf16 v[90:93], v[170:173], v[150:153], v[90:93]
	v_mfma_f32_16x16x32_bf16 v[94:97], v[174:177], v[150:153], v[94:97]
	v_mfma_f32_16x16x32_bf16 v[98:101], v[162:165], v[154:157], v[98:101]
	v_mfma_f32_16x16x32_bf16 v[102:105], v[166:169], v[154:157], v[102:105]
	v_mfma_f32_16x16x32_bf16 v[106:109], v[170:173], v[154:157], v[106:109]
	v_mfma_f32_16x16x32_bf16 v[110:113], v[174:177], v[154:157], v[110:113]
	v_mfma_f32_16x16x32_bf16 v[114:117], v[162:165], v[158:161], v[114:117]
	v_mfma_f32_16x16x32_bf16 v[118:121], v[166:169], v[158:161], v[118:121]
	v_mfma_f32_16x16x32_bf16 v[122:125], v[170:173], v[158:161], v[122:125]
	v_mfma_f32_16x16x32_bf16 v[126:129], v[174:177], v[158:161], v[126:129]
	s_setprio 0
	s_add_i32 s60, s60, 0x6000
	s_cmp_eq_u32 s60, 0x12000
	s_cselect_b32 s60, 0, s60
	s_add_u32 s54, s54, s72
	s_addc_u32 s55, s55, 0
	s_add_u32 s56, s56, s73
	s_addc_u32 s57, s57, 0
	s_add_i32 s61, s61, 0x6000
	s_cmp_eq_u32 s61, 0x12000
	s_cselect_b32 s61, 0, s61
	v_mov_b32_e32 v226, v232
	v_mov_b32_e32 v230, v236
	v_mov_b32_e32 v231, v237
	s_mov_b64 s[54:55], s[48:49]
	s_mov_b64 s[56:57], s[50:51]
	s_waitcnt vmcnt(6) lgkmcnt(0)
	s_barrier
	v_add_u32_e32 v240, s61, v238
	v_add_u32_e32 v241, s61, v239
	s_add_i32 m0, s60, s62
	v_mfma_f32_16x16x32_bf16 v[2:5], v[210:213], v[178:181], v[2:5]
	global_load_lds_dwordx4 v226, s[54:55]
	v_mfma_f32_16x16x32_bf16 v[6:9], v[214:217], v[178:181], v[6:9]
	global_load_lds_dwordx4 v226, s[54:55] offset:1024
	v_mfma_f32_16x16x32_bf16 v[10:13], v[218:221], v[178:181], v[10:13]
	global_load_lds_dwordx4 v226, s[54:55] offset:2048
	v_mfma_f32_16x16x32_bf16 v[14:17], v[222:225], v[178:181], v[14:17]
	global_load_lds_dwordx4 v226, s[54:55] offset:3072
	s_add_i32 m0, s60, s63
	v_mfma_f32_16x16x32_bf16 v[18:21], v[210:213], v[182:185], v[18:21]
	global_load_lds_dwordx4 v230, s[56:57]
	v_mfma_f32_16x16x32_bf16 v[22:25], v[214:217], v[182:185], v[22:25]
	global_load_lds_dwordx4 v231, s[56:57] offset:1024
	v_mfma_f32_16x16x32_bf16 v[26:29], v[218:221], v[182:185], v[26:29]
	v_mfma_f32_16x16x32_bf16 v[30:33], v[222:225], v[182:185], v[30:33]
	v_mfma_f32_16x16x32_bf16 v[34:37], v[210:213], v[186:189], v[34:37]
	ds_read_b128 v[162:165], v241 offset:0
	v_mfma_f32_16x16x32_bf16 v[38:41], v[214:217], v[186:189], v[38:41]
	ds_read_b128 v[166:169], v241 offset:256
	v_mfma_f32_16x16x32_bf16 v[42:45], v[218:221], v[186:189], v[42:45]
	ds_read_b128 v[170:173], v241 offset:2048
	v_mfma_f32_16x16x32_bf16 v[46:49], v[222:225], v[186:189], v[46:49]
	ds_read_b128 v[174:177], v241 offset:2304
	v_mfma_f32_16x16x32_bf16 v[50:53], v[210:213], v[190:193], v[50:53]
	ds_read_b128 v[130:133], v240 offset:0
	v_mfma_f32_16x16x32_bf16 v[54:57], v[214:217], v[190:193], v[54:57]
	ds_read_b128 v[134:137], v240 offset:1024
	v_mfma_f32_16x16x32_bf16 v[58:61], v[218:221], v[190:193], v[58:61]
	ds_read_b128 v[138:141], v240 offset:2048
	v_mfma_f32_16x16x32_bf16 v[62:65], v[222:225], v[190:193], v[62:65]
	ds_read_b128 v[142:145], v240 offset:3072
	v_mfma_f32_16x16x32_bf16 v[66:69], v[210:213], v[194:197], v[66:69]
	ds_read_b128 v[146:149], v240 offset:4096
	v_mfma_f32_16x16x32_bf16 v[70:73], v[214:217], v[194:197], v[70:73]
	ds_read_b128 v[150:153], v240 offset:5120
	v_mfma_f32_16x16x32_bf16 v[74:77], v[218:221], v[194:197], v[74:77]
	ds_read_b128 v[154:157], v240 offset:6144
	v_mfma_f32_16x16x32_bf16 v[78:81], v[222:225], v[194:197], v[78:81]
	ds_read_b128 v[158:161], v240 offset:7168
	s_setprio 1
	v_mfma_f32_16x16x32_bf16 v[82:85], v[210:213], v[198:201], v[82:85]
	v_mfma_f32_16x16x32_bf16 v[86:89], v[214:217], v[198:201], v[86:89]
	v_mfma_f32_16x16x32_bf16 v[90:93], v[218:221], v[198:201], v[90:93]
	v_mfma_f32_16x16x32_bf16 v[94:97], v[222:225], v[198:201], v[94:97]
	v_mfma_f32_16x16x32_bf16 v[98:101], v[210:213], v[202:205], v[98:101]
	v_mfma_f32_16x16x32_bf16 v[102:105], v[214:217], v[202:205], v[102:105]
	v_mfma_f32_16x16x32_bf16 v[106:109], v[218:221], v[202:205], v[106:109]
	v_mfma_f32_16x16x32_bf16 v[110:113], v[222:225], v[202:205], v[110:113]
	v_mfma_f32_16x16x32_bf16 v[114:117], v[210:213], v[206:209], v[114:117]
	v_mfma_f32_16x16x32_bf16 v[118:121], v[214:217], v[206:209], v[118:121]
	v_mfma_f32_16x16x32_bf16 v[122:125], v[218:221], v[206:209], v[122:125]
	v_mfma_f32_16x16x32_bf16 v[126:129], v[222:225], v[206:209], v[126:129]
	s_setprio 0
	s_add_i32 s60, s60, 0x6000
	s_cmp_eq_u32 s60, 0x12000
	s_cselect_b32 s60, 0, s60
	s_add_u32 s54, s54, s72
	s_addc_u32 s55, s55, 0
	s_add_u32 s56, s56, s73
	s_addc_u32 s57, s57, 0
	s_add_i32 s61, s61, 0x6000
	s_cmp_eq_u32 s61, 0x12000
	s_cselect_b32 s61, 0, s61
	s_waitcnt vmcnt(6) lgkmcnt(0)
	s_barrier
	v_add_u32_e32 v240, s61, v238
	v_add_u32_e32 v241, s61, v239
	s_add_i32 m0, s60, s62
	v_mfma_f32_16x16x32_bf16 v[2:5], v[162:165], v[130:133], v[2:5]
	global_load_lds_dwordx4 v226, s[54:55]
	v_mfma_f32_16x16x32_bf16 v[6:9], v[166:169], v[130:133], v[6:9]
	global_load_lds_dwordx4 v226, s[54:55] offset:1024
	v_mfma_f32_16x16x32_bf16 v[10:13], v[170:173], v[130:133], v[10:13]
	global_load_lds_dwordx4 v226, s[54:55] offset:2048
	v_mfma_f32_16x16x32_bf16 v[14:17], v[174:177], v[130:133], v[14:17]
	global_load_lds_dwordx4 v226, s[54:55] offset:3072
	s_add_i32 m0, s60, s63
	v_mfma_f32_16x16x32_bf16 v[18:21], v[162:165], v[134:137], v[18:21]
	global_load_lds_dwordx4 v230, s[56:57]
	v_mfma_f32_16x16x32_bf16 v[22:25], v[166:169], v[134:137], v[22:25]
	global_load_lds_dwordx4 v231, s[56:57] offset:1024
	v_mfma_f32_16x16x32_bf16 v[26:29], v[170:173], v[134:137], v[26:29]
	v_mfma_f32_16x16x32_bf16 v[30:33], v[174:177], v[134:137], v[30:33]
	v_mfma_f32_16x16x32_bf16 v[34:37], v[162:165], v[138:141], v[34:37]
	ds_read_b128 v[210:213], v241 offset:0
	v_mfma_f32_16x16x32_bf16 v[38:41], v[166:169], v[138:141], v[38:41]
	ds_read_b128 v[214:217], v241 offset:256
	v_mfma_f32_16x16x32_bf16 v[42:45], v[170:173], v[138:141], v[42:45]
	ds_read_b128 v[218:221], v241 offset:2048
	v_mfma_f32_16x16x32_bf16 v[46:49], v[174:177], v[138:141], v[46:49]
	ds_read_b128 v[222:225], v241 offset:2304
	v_mfma_f32_16x16x32_bf16 v[50:53], v[162:165], v[142:145], v[50:53]
	ds_read_b128 v[178:181], v240 offset:0
	v_mfma_f32_16x16x32_bf16 v[54:57], v[166:169], v[142:145], v[54:57]
	ds_read_b128 v[182:185], v240 offset:1024
	v_mfma_f32_16x16x32_bf16 v[58:61], v[170:173], v[142:145], v[58:61]
	ds_read_b128 v[186:189], v240 offset:2048
	v_mfma_f32_16x16x32_bf16 v[62:65], v[174:177], v[142:145], v[62:65]
	ds_read_b128 v[190:193], v240 offset:3072
	v_mfma_f32_16x16x32_bf16 v[66:69], v[162:165], v[146:149], v[66:69]
	ds_read_b128 v[194:197], v240 offset:4096
	v_mfma_f32_16x16x32_bf16 v[70:73], v[166:169], v[146:149], v[70:73]
	ds_read_b128 v[198:201], v240 offset:5120
	v_mfma_f32_16x16x32_bf16 v[74:77], v[170:173], v[146:149], v[74:77]
	ds_read_b128 v[202:205], v240 offset:6144
	v_mfma_f32_16x16x32_bf16 v[78:81], v[174:177], v[146:149], v[78:81]
	ds_read_b128 v[206:209], v240 offset:7168
	s_setprio 1
	v_mfma_f32_16x16x32_bf16 v[82:85], v[162:165], v[150:153], v[82:85]
	v_mfma_f32_16x16x32_bf16 v[86:89], v[166:169], v[150:153], v[86:89]
	v_mfma_f32_16x16x32_bf16 v[90:93], v[170:173], v[150:153], v[90:93]
	v_mfma_f32_16x16x32_bf16 v[94:97], v[174:177], v[150:153], v[94:97]
	v_mfma_f32_16x16x32_bf16 v[98:101], v[162:165], v[154:157], v[98:101]
	v_mfma_f32_16x16x32_bf16 v[102:105], v[166:169], v[154:157], v[102:105]
	v_mfma_f32_16x16x32_bf16 v[106:109], v[170:173], v[154:157], v[106:109]
	v_mfma_f32_16x16x32_bf16 v[110:113], v[174:177], v[154:157], v[110:113]
	v_mfma_f32_16x16x32_bf16 v[114:117], v[162:165], v[158:161], v[114:117]
	v_mfma_f32_16x16x32_bf16 v[118:121], v[166:169], v[158:161], v[118:121]
	v_mfma_f32_16x16x32_bf16 v[122:125], v[170:173], v[158:161], v[122:125]
	v_mfma_f32_16x16x32_bf16 v[126:129], v[174:177], v[158:161], v[126:129]
	s_setprio 0
	s_add_i32 s60, s60, 0x6000
	s_cmp_eq_u32 s60, 0x12000
	s_cselect_b32 s60, 0, s60
	s_add_u32 s54, s54, s72
	s_addc_u32 s55, s55, 0
	s_add_u32 s56, s56, s73
	s_addc_u32 s57, s57, 0
	s_add_i32 s61, s61, 0x6000
	s_cmp_eq_u32 s61, 0x12000
	s_cselect_b32 s61, 0, s61
	s_waitcnt vmcnt(6) lgkmcnt(0)
	s_barrier
	v_add_u32_e32 v240, s61, v238
	v_add_u32_e32 v241, s61, v239
	s_add_i32 m0, s60, s62
	v_mfma_f32_16x16x32_bf16 v[2:5], v[210:213], v[178:181], v[2:5]
	global_load_lds_dwordx4 v226, s[54:55]
	v_mfma_f32_16x16x32_bf16 v[6:9], v[214:217], v[178:181], v[6:9]
	global_load_lds_dwordx4 v226, s[54:55] offset:1024
	v_mfma_f32_16x16x32_bf16 v[10:13], v[218:221], v[178:181], v[10:13]
	global_load_lds_dwordx4 v226, s[54:55] offset:2048
	v_mfma_f32_16x16x32_bf16 v[14:17], v[222:225], v[178:181], v[14:17]
	global_load_lds_dwordx4 v226, s[54:55] offset:3072
	s_add_i32 m0, s60, s63
	v_mfma_f32_16x16x32_bf16 v[18:21], v[210:213], v[182:185], v[18:21]
	global_load_lds_dwordx4 v230, s[56:57]
	v_mfma_f32_16x16x32_bf16 v[22:25], v[214:217], v[182:185], v[22:25]
	global_load_lds_dwordx4 v231, s[56:57] offset:1024
	v_mfma_f32_16x16x32_bf16 v[26:29], v[218:221], v[182:185], v[26:29]
	v_mfma_f32_16x16x32_bf16 v[30:33], v[222:225], v[182:185], v[30:33]
	v_mfma_f32_16x16x32_bf16 v[34:37], v[210:213], v[186:189], v[34:37]
	ds_read_b128 v[162:165], v241 offset:0
	v_mfma_f32_16x16x32_bf16 v[38:41], v[214:217], v[186:189], v[38:41]
	ds_read_b128 v[166:169], v241 offset:256
	v_mfma_f32_16x16x32_bf16 v[42:45], v[218:221], v[186:189], v[42:45]
	ds_read_b128 v[170:173], v241 offset:2048
	v_mfma_f32_16x16x32_bf16 v[46:49], v[222:225], v[186:189], v[46:49]
	ds_read_b128 v[174:177], v241 offset:2304
	v_mfma_f32_16x16x32_bf16 v[50:53], v[210:213], v[190:193], v[50:53]
	ds_read_b128 v[130:133], v240 offset:0
	v_mfma_f32_16x16x32_bf16 v[54:57], v[214:217], v[190:193], v[54:57]
	ds_read_b128 v[134:137], v240 offset:1024
	v_mfma_f32_16x16x32_bf16 v[58:61], v[218:221], v[190:193], v[58:61]
	ds_read_b128 v[138:141], v240 offset:2048
	v_mfma_f32_16x16x32_bf16 v[62:65], v[222:225], v[190:193], v[62:65]
	ds_read_b128 v[142:145], v240 offset:3072
	v_mfma_f32_16x16x32_bf16 v[66:69], v[210:213], v[194:197], v[66:69]
	ds_read_b128 v[146:149], v240 offset:4096
	v_mfma_f32_16x16x32_bf16 v[70:73], v[214:217], v[194:197], v[70:73]
	ds_read_b128 v[150:153], v240 offset:5120
	v_mfma_f32_16x16x32_bf16 v[74:77], v[218:221], v[194:197], v[74:77]
	ds_read_b128 v[154:157], v240 offset:6144
	v_mfma_f32_16x16x32_bf16 v[78:81], v[222:225], v[194:197], v[78:81]
	ds_read_b128 v[158:161], v240 offset:7168
	s_setprio 1
	v_mfma_f32_16x16x32_bf16 v[82:85], v[210:213], v[198:201], v[82:85]
	v_mfma_f32_16x16x32_bf16 v[86:89], v[214:217], v[198:201], v[86:89]
	v_mfma_f32_16x16x32_bf16 v[90:93], v[218:221], v[198:201], v[90:93]
	v_mfma_f32_16x16x32_bf16 v[94:97], v[222:225], v[198:201], v[94:97]
	v_mfma_f32_16x16x32_bf16 v[98:101], v[210:213], v[202:205], v[98:101]
	v_mfma_f32_16x16x32_bf16 v[102:105], v[214:217], v[202:205], v[102:105]
	v_mfma_f32_16x16x32_bf16 v[106:109], v[218:221], v[202:205], v[106:109]
	v_mfma_f32_16x16x32_bf16 v[110:113], v[222:225], v[202:205], v[110:113]
	v_mfma_f32_16x16x32_bf16 v[114:117], v[210:213], v[206:209], v[114:117]
	v_mfma_f32_16x16x32_bf16 v[118:121], v[214:217], v[206:209], v[118:121]
	v_mfma_f32_16x16x32_bf16 v[122:125], v[218:221], v[206:209], v[122:125]
	v_mfma_f32_16x16x32_bf16 v[126:129], v[222:225], v[206:209], v[126:129]
	s_setprio 0
	s_add_i32 s60, s60, 0x6000
	s_cmp_eq_u32 s60, 0x12000
	s_cselect_b32 s60, 0, s60
	s_add_u32 s54, s54, s72
	s_addc_u32 s55, s55, 0
	s_add_u32 s56, s56, s73
	s_addc_u32 s57, s57, 0
	s_add_i32 s61, s61, 0x6000
	s_cmp_eq_u32 s61, 0x12000
	s_cselect_b32 s61, 0, s61
	s_branch .Lpj_epi

.Lop_entry:
	s_waitcnt lgkmcnt(0)
	s_load_dwordx2 s[48:49], s[0:1], 0xc0
	s_load_dwordx2 s[50:51], s[0:1], 0xa0
	s_load_dwordx2 s[52:53], s[0:1], 0x110
	s_mov_b32 s59, 32
	s_mov_b32 s72, 0x100000
	s_mov_b32 s73, 0x10000
	s_movk_i32 s32, 0x200
	v_and_b32_e32 v0, 63, v154
	v_lshrrev_b32_e32 v131, 6, v154
	v_lshrrev_b32_e32 v243, 2, v0
	v_readfirstlane_b32 s41, v131
	v_and_b32_e32 v130, 3, v0
	v_mov_b32_e32 v134, 0x1320
	s_nop 1
	s_lshr_b32 s42, s41, 1
	s_and_b32 s43, s41, 1
	v_bfe_u32 v132, v0, 4, 2
	v_lshlrev_b32_e32 v132, 2, v132
	v_lshrrev_b32_e32 v132, v132, v134
	v_and_b32_e32 v132, 3, v132
	v_xor_b32_e32 v132, v132, v130
	v_lshlrev_b32_e32 v245, 4, v132
	v_bfe_u32 v132, v0, 2, 2
	v_lshlrev_b32_e32 v132, 2, v132
	v_lshrrev_b32_e32 v132, v132, v134
	v_and_b32_e32 v132, 3, v132
	v_lshrrev_b32_e32 v133, 4, v0
	v_xor_b32_e32 v132, v132, v133
	v_lshlrev_b32_e32 v132, 4, v132
	v_and_b32_e32 v131, 15, v0
	s_lshl_b32 s26, s42, 13
	v_lshl_add_u32 v238, v131, 6, v132
	v_add_u32_e32 v238, s26, v238
	s_lshl_b32 s62, s41, 12
	s_lshl_b32 s63, s41, 11
	s_add_i32 s63, s63, 0x4000
	s_lshl_b32 s26, s43, 12
	s_add_i32 s26, s26, 0x4000
	v_lshrrev_b32_e32 v134, 2, v131
	v_lshl_add_u32 v239, v134, 10, v132
	v_and_b32_e32 v134, 3, v131
	v_lshl_add_u32 v239, v134, 6, v239
	v_add_u32_e32 v239, s26, v239
	s_lshl_b32 s26, s41, 1
	s_and_b32 s26, s26, 3
	s_lshl_b32 s26, s26, 2
	s_lshr_b32 s26, 0x1320, s26
	s_and_b32 s26, s26, 3
	v_xor_b32_e32 v246, s26, v130
	v_lshlrev_b32_e32 v246, 4, v246
	s_lshl_b32 s26, s41, 1
	s_add_i32 s26, s26, 1
	s_and_b32 s26, s26, 3
	s_lshl_b32 s26, s26, 2
	s_lshr_b32 s26, 0x1320, s26
	s_and_b32 s26, s26, 3
	v_xor_b32_e32 v247, s26, v130
	v_lshlrev_b32_e32 v247, 4, v247
	v_lshlrev_b32_e32 v133, 5, v133
	v_lshl_add_u32 v242, v131, 11, v133
	s_lshl_b32 s26, s42, 18
	s_lshl_b32 s27, s43, 7
	s_add_i32 s26, s26, s27
	v_add_u32_e32 v242, s26, v242
	s_mov_b32 s34, s3
	s_cmp_lt_i32 s34, s32
	s_cbranch_scc0 .Lop_done
	s_and_b32 s26, s34, 7
	s_lshr_b32 s27, s34, 3
	s_lshr_b32 s36, s27, 3
	s_and_b32 s27, s27, 7
	s_lshl_b32 s27, s27, 3
	s_add_i32 s35, s27, s26
	s_lshl_b32 s35, s35, 8
	s_lshl_b32 s36, s36, 7
	s_lshl_b32 s26, s41, 6
	s_add_i32 s26, s26, s35
	v_add_u32_e32 v0, s26, v243
	v_lshl_add_u32 v226, v0, 6, v245
	s_lshl_b32 s26, s41, 5
	s_add_i32 s26, s26, s36
	v_add_u32_e32 v0, s26, v243
	v_lshl_add_u32 v230, v0, 6, v246
	v_lshl_add_u32 v231, v0, 6, v247
	s_mov_b32 s60, 0
	s_mov_b32 s61, 0
	s_waitcnt lgkmcnt(0)
	s_mov_b64 s[54:55], s[48:49]
	s_mov_b64 s[56:57], s[50:51]
	s_add_i32 m0, s60, s62
	s_nop 0
	global_load_lds_dwordx4 v226, s[54:55]
	global_load_lds_dwordx4 v226, s[54:55] offset:1024
	global_load_lds_dwordx4 v226, s[54:55] offset:2048
	global_load_lds_dwordx4 v226, s[54:55] offset:3072
	s_add_i32 m0, s60, s63
	s_nop 0
	global_load_lds_dwordx4 v230, s[56:57]
	global_load_lds_dwordx4 v231, s[56:57] offset:1024
	s_add_i32 s60, s60, 0x6000
	s_cmp_eq_u32 s60, 0x12000
	s_cselect_b32 s60, 0, s60
	s_add_u32 s54, s54, s72
	s_addc_u32 s55, s55, 0
	s_add_u32 s56, s56, s73
	s_addc_u32 s57, s57, 0
	s_add_i32 m0, s60, s62
	s_nop 0
	global_load_lds_dwordx4 v226, s[54:55]
	global_load_lds_dwordx4 v226, s[54:55] offset:1024
	global_load_lds_dwordx4 v226, s[54:55] offset:2048
	global_load_lds_dwordx4 v226, s[54:55] offset:3072
	s_add_i32 m0, s60, s63
	s_nop 0
	global_load_lds_dwordx4 v230, s[56:57]
	global_load_lds_dwordx4 v231, s[56:57] offset:1024
	s_add_i32 s60, s60, 0x6000
	s_cmp_eq_u32 s60, 0x12000
	s_cselect_b32 s60, 0, s60
	s_add_u32 s54, s54, s72
	s_addc_u32 s55, s55, 0
	s_add_u32 s56, s56, s73
	s_addc_u32 s57, s57, 0
	s_add_i32 m0, s60, s62
	s_nop 0
	global_load_lds_dwordx4 v226, s[54:55]
	global_load_lds_dwordx4 v226, s[54:55] offset:1024
	global_load_lds_dwordx4 v226, s[54:55] offset:2048
	global_load_lds_dwordx4 v226, s[54:55] offset:3072
	s_add_i32 m0, s60, s63
	s_nop 0
	global_load_lds_dwordx4 v230, s[56:57]
	global_load_lds_dwordx4 v231, s[56:57] offset:1024
	s_add_i32 s60, s60, 0x6000
	s_cmp_eq_u32 s60, 0x12000
	s_cselect_b32 s60, 0, s60
	s_add_u32 s54, s54, s72
	s_addc_u32 s55, s55, 0
	s_add_u32 s56, s56, s73
	s_addc_u32 s57, s57, 0
	s_waitcnt vmcnt(12)
	s_barrier
	v_add_u32_e32 v240, s61, v238
	v_add_u32_e32 v241, s61, v239
	ds_read_b128 v[162:165], v241 offset:0
	ds_read_b128 v[166:169], v241 offset:256
	ds_read_b128 v[170:173], v241 offset:512
	ds_read_b128 v[174:177], v241 offset:768
	ds_read_b128 v[130:133], v240 offset:0
	ds_read_b128 v[134:137], v240 offset:1024
	ds_read_b128 v[138:141], v240 offset:2048
	ds_read_b128 v[142:145], v240 offset:3072
	ds_read_b128 v[146:149], v240 offset:4096
	ds_read_b128 v[150:153], v240 offset:5120
	ds_read_b128 v[154:157], v240 offset:6144
	ds_read_b128 v[158:161], v240 offset:7168
	s_add_i32 s61, s61, 0x6000
	s_cmp_eq_u32 s61, 0x12000
	s_cselect_b32 s61, 0, s61
	s_add_i32 s38, s34, s71
	s_cmp_lt_i32 s38, s32
	s_cselect_b32 s37, 1, 0
	s_cbranch_scc0 .Lop_nn_a
	s_and_b32 s26, s38, 7
	s_lshr_b32 s27, s38, 3
	s_lshr_b32 s31, s27, 3
	s_and_b32 s27, s27, 7
	s_lshl_b32 s27, s27, 3
	s_add_i32 s30, s27, s26
	s_lshl_b32 s30, s30, 8
	s_lshl_b32 s31, s31, 7
	s_lshl_b32 s26, s41, 6
	s_add_i32 s26, s26, s30
	v_add_u32_e32 v0, s26, v243
	v_lshl_add_u32 v232, v0, 6, v245
	s_lshl_b32 s26, s41, 5
	s_add_i32 s26, s26, s31
	v_add_u32_e32 v0, s26, v243
	v_lshl_add_u32 v236, v0, 6, v246
	v_lshl_add_u32 v237, v0, 6, v247

	.amdhsa_kernel _Z11mega_kernel6Params
		.amdhsa_group_segment_fixed_size 78864
		.amdhsa_private_segment_fixed_size 0
		.amdhsa_kernarg_size 568
		.amdhsa_user_sgpr_count 2
		.amdhsa_user_sgpr_dispatch_ptr 0
		.amdhsa_user_sgpr_queue_ptr 0
		.amdhsa_user_sgpr_kernarg_segment_ptr 1
		.amdhsa_user_sgpr_dispatch_id 0
		.amdhsa_user_sgpr_kernarg_preload_length 0
		.amdhsa_user_sgpr_kernarg_preload_offset 0
		.amdhsa_user_sgpr_private_segment_size 0
		.amdhsa_uses_dynamic_stack 0
		.amdhsa_enable_private_segment 0
		.amdhsa_system_sgpr_workgroup_id_x 1
		.amdhsa_system_sgpr_workgroup_id_y 0
		.amdhsa_system_sgpr_workgroup_id_z 0
		.amdhsa_system_sgpr_workgroup_info 0
		.amdhsa_system_vgpr_workitem_id 2
		.amdhsa_next_free_vgpr 251
		.amdhsa_next_free_sgpr 100
		.amdhsa_accum_offset 252
		.amdhsa_reserve_vcc 1
		.amdhsa_float_round_mode_32 0
		.amdhsa_float_round_mode_16_64 0
		.amdhsa_float_denorm_mode_32 3
		.amdhsa_float_denorm_mode_16_64 3
		.amdhsa_dx10_clamp 1
		.amdhsa_ieee_mode 1
		.amdhsa_fp16_overflow 0
		.amdhsa_tg_split 0
		.amdhsa_exception_fp_ieee_invalid_op 0
		.amdhsa_exception_fp_denorm_src 0
		.amdhsa_exception_fp_ieee_div_zero 0
		.amdhsa_exception_fp_ieee_overflow 0
		.amdhsa_exception_fp_ieee_underflow 0
		.amdhsa_exception_fp_ieee_inexact 0
		.amdhsa_exception_int_div_zero 0
	.end_amdhsa_kernel

amdhsa.kernels:
  - .agpr_count:     0
    .args:
      - .offset:         0
        .size:           312
        .value_kind:     by_value
      - .offset:         312
        .size:           4
        .value_kind:     hidden_block_count_x
      - .offset:         316
        .size:           4
        .value_kind:     hidden_block_count_y
      - .offset:         320
        .size:           4
        .value_kind:     hidden_block_count_z
      - .offset:         324
        .size:           2
        .value_kind:     hidden_group_size_x
      - .offset:         326
        .size:           2
        .value_kind:     hidden_group_size_y
      - .offset:         328
        .size:           2
        .value_kind:     hidden_group_size_z
      - .offset:         330
        .size:           2
        .value_kind:     hidden_remainder_x
      - .offset:         332
        .size:           2
        .value_kind:     hidden_remainder_y
      - .offset:         334
        .size:           2
        .value_kind:     hidden_remainder_z
      - .offset:         352
        .size:           8
        .value_kind:     hidden_global_offset_x
      - .offset:         360
        .size:           8
        .value_kind:     hidden_global_offset_y
      - .offset:         368
        .size:           8
        .value_kind:     hidden_global_offset_z
      - .offset:         376
        .size:           2
        .value_kind:     hidden_grid_dims
      - .offset:         400
        .size:           8
        .value_kind:     hidden_multigrid_sync_arg
    .group_segment_fixed_size: 78864
    .kernarg_segment_align: 8
    .kernarg_segment_size: 568
    .language:       OpenCL C
    .language_version:
      - 2
      - 0
    .max_flat_workgroup_size: 256
    .name:           _Z11mega_kernel6Params
    .private_segment_fixed_size: 0
    .sgpr_count:     106
    .sgpr_spill_count: 74
    .symbol:         _Z11mega_kernel6Params.kd
    .uniform_work_group_size: 1
    .uses_dynamic_stack: false
    .vgpr_count:     251
    .vgpr_spill_count: 0
    .wavefront_size: 64
